# NA: waves map to 16 query columns x 2 grid rows, so a window tile needs one 32-key block per wave (4 QK + 4 PV MFMAs instead of 8 + 6); per-lane first-tile anchoring; rows outside a query row's window
# speedup vs baseline: 1.0281x; 1.0087x over previous
.Lna_noremap:
	s_and_b32 s11, s8, 3
	s_lshr_b32 s68, s8, 2
	s_lshl_b32 s36, s11, 3
	s_cmp_ge_u32 s11, 2
	s_cselect_b32 s37, 8, 0
	s_add_i32 s66, s36, s37
	s_lshl_b32 s36, s11, 4
	s_sub_i32 s67, s66, s36
	s_mov_b32 s64, 0xffff
	s_mov_b32 s65, 0xffff
	v_and_b32_e32 v216, 31, v0
	v_bfe_u32 v217, v0, 5, 1
	v_mov_b32_e32 v228, 0
	v_mov_b32_e32 v229, 0xf149f2ca
	v_add_u32_e32 v222, s66, v216
	v_mul_u32_u24_e32 v199, 0x90, v222
	v_lshl_add_u32 v199, v217, 4, v199
	v_mul_u32_u24_e32 v200, 0x90, v216
	v_lshl_add_u32 v200, v217, 4, v200
	v_mul_u32_u24_e32 v222, 0x88, v216
	v_lshl_add_u32 v222, v217, 3, v222
	v_add_u32_e32 v202, 0x4800, v222
	s_lshl_b32 s36, s66, 1
	v_add_u32_e32 v201, s36, v202
	v_lshrrev_b32_e32 v222, 3, v0
	v_and_b32_e32 v223, 7, v0
	v_mul_u32_u24_e32 v204, 0x90, v222
	v_lshl_add_u32 v204, v223, 4, v204
	v_mul_u32_u24_e32 v205, 0x88, v222
	v_lshl_add_u32 v205, v223, 4, v205
	v_add_u32_e32 v205, 0x4800, v205
	v_lshlrev_b32_e32 v206, 4, v0
	v_mul_u32_u24_e32 v207, 0x2200, v222
	v_lshl_add_u32 v207, v223, 4, v207
	v_bfe_u32 v224, v0, 4, 1
	v_and_b32_e32 v225, 15, v0
	s_lshl_b32 s36, s68, 1
	v_add_u32_e32 v222, s36, v224
	s_lshl_b32 s36, s11, 4
	v_add_u32_e32 v223, s36, v225
	v_lshl_add_u32 v222, v222, 6, v223
	v_lshlrev_b32_e32 v219, 7, v222
	v_lshl_add_u32 v219, v217, 4, v219
	v_lshlrev_b32_e32 v218, 10, v222
	v_lshl_add_u32 v218, v217, 3, v218
	v_and_b32_e32 v222, 3, v225
	v_add_u32_e32 v223, 1, v222
	v_and_b32_e32 v223, 3, v223
	v_lshl_add_u32 v223, v217, 2, v223
	v_sub_u32_e32 v223, v223, v225
	s_add_i32 s36, s67, 39
	v_add_u32_e32 v223, s36, v223
	v_mul_u32_u24_e32 v226, 84, v224
	v_sub_u32_e32 v223, v223, v226
	v_lshlrev_b32_e32 v223, 2, v223
	v_mul_u32_u24_e32 v222, 5040, v222
	v_add_u32_e32 v208, v222, v223
	v_add_u32_e32 v208, 0x8c00, v208
	s_lshr_b32 s36, s10, 4
	s_and_b32 s37, s10, 15
	s_mul_i32 s38, s36, 0x88000
	s_add_u32 s38, s38, 0x4700000
	s_add_u32 s12, s4, s38
	s_addc_u32 s13, s5, 0
	s_add_u32 s38, s38, 0x1100000
	s_add_u32 s14, s4, s38
	s_addc_u32 s15, s5, 0
	s_add_u32 s16, s12, 0x80000
	s_addc_u32 s17, s13, 0
	s_add_u32 s18, s14, 0x2000
	s_addc_u32 s19, s15, 0
	s_lshl_b32 s40, s68, 1
	s_add_i32 s38, s37, -1
	s_cmp_lt_u32 s38, 14
	s_cselect_b32 s22, 12, 8
	s_cselect_b32 s39, 1, 0
	s_lshl_b32 s41, s37, 2
	s_add_i32 s42, s41, -4
	s_max_i32 s42, s42, 0
	s_min_i32 s42, s42, 56
	s_sub_i32 s42, s42, s39
	s_add_i32 s43, s41, s40
	s_add_i32 s23, s43, -4
	s_max_i32 s23, s23, 0
	s_min_i32 s23, s23, 56
	s_add_i32 s62, s43, -3
	s_max_i32 s62, s62, 0
	s_min_i32 s62, s62, 56
	s_sub_i32 s62, s62, s23
	s_add_i32 s63, s62, 8
	s_sub_i32 s23, s23, s42
	s_sub_i32 s43, s42, s43
	s_add_i32 s43, s43, 7
	s_mul_i32 s25, s43, 0x150
	s_ashr_i32 s43, s42, 31
	s_lshl_b64 s[44:45], s[42:43], 13
	s_add_u32 s12, s12, s44
	s_addc_u32 s13, s13, s45
	s_lshl_b64 s[44:45], s[42:43], 7
	s_add_u32 s14, s14, s44
	s_addc_u32 s15, s15, s45
	s_lshl_b32 s38, s36, 12
	s_lshl_b32 s39, s37, 8
	s_add_u32 s38, s38, s39
	s_lshl_b32 s38, s38, 7
	s_add_u32 s38, s38, 0x6900000
	s_add_u32 s34, s4, s38
	s_addc_u32 s35, s5, 0
	s_lshr_b32 s38, s36, 3
	s_lshl_b32 s38, s38, 12
	s_add_u32 s38, s38, s39
	s_lshl_b32 s38, s38, 10
	s_and_b32 s40, s36, 7
	s_lshl_b32 s40, s40, 7
	s_add_u32 s38, s38, s40
	s_add_u32 s38, s38, 0x8900000
	s_add_u32 s30, s4, s38
	s_addc_u32 s31, s5, 0
	global_load_dwordx4 v[98:101], v219, s[34:35] offset:0
	global_load_dwordx4 v[102:105], v219, s[34:35] offset:32
	global_load_dwordx4 v[106:109], v219, s[34:35] offset:64
	global_load_dwordx4 v[110:113], v219, s[34:35] offset:96
	global_load_dwordx4 v[34:37], v206, s[12:13]
	s_add_u32 s12, s12, 0x2000
	s_addc_u32 s13, s13, 0
	global_load_dwordx4 v[230:233], v206, s[12:13]
	global_load_dwordx4 v[234:237], v207, s[14:15]
	s_add_u32 s12, s12, 0x2000
	s_addc_u32 s13, s13, 0
	s_add_u32 s14, s14, 0x80
	s_addc_u32 s15, s15, 0
	global_load_dwordx4 v[188:191], v206, s[12:13]
	global_load_dwordx4 v[192:195], v207, s[14:15]
	s_add_u32 s12, s12, 0x2000
	s_addc_u32 s13, s13, 0
	s_add_u32 s14, s14, 0x80
	s_addc_u32 s15, s15, 0
	s_mov_b32 s20, 3
	s_mov_b32 s21, 2
	s_lshr_b32 s36, s10, 4
	s_and_b32 s36, s36, 7
	s_mul_i32 s36, s36, 0x744
	s_add_u32 s38, s6, s36
	s_addc_u32 s39, s7, 0
	s_mov_b32 s36, 0xd00e
	v_mov_b32_e32 v222, v0
	v_mul_lo_u32 v223, v222, s36
	v_lshrrev_b32_e32 v223, 26, v223
	v_mul_u32_u24_e32 v224, 1260, v223
	v_sub_u32_e32 v224, v222, v224
	v_mul_u32_u24_e32 v225, 49933, v224
	v_lshrrev_b32_e32 v225, 22, v225
	v_mul_u32_u24_e32 v226, 84, v225
	v_sub_u32_e32 v226, v224, v226
	v_add_u32_e32 v227, 1, v223
	v_and_b32_e32 v227, 3, v227
	v_sub_u32_e32 v226, v226, v227
	v_subrev_u32_e32 v226, 24, v226
	v_cmp_gt_u32_e64 s[40:41], 31, v226
	s_nop 1
	v_cndmask_b32_e64 v227, 0, v226, s[40:41]
	v_mad_u32_u24 v227, v225, 31, v227
	v_lshlrev_b32_e32 v227, 2, v227
	global_load_dword v40, v227, s[38:39]
	v_add_u32_e32 v222, 512, v0
	v_mul_lo_u32 v223, v222, s36
	v_lshrrev_b32_e32 v223, 26, v223
	v_mul_u32_u24_e32 v224, 1260, v223
	v_sub_u32_e32 v224, v222, v224
	v_mul_u32_u24_e32 v225, 49933, v224
	v_lshrrev_b32_e32 v225, 22, v225
	v_mul_u32_u24_e32 v226, 84, v225
	v_sub_u32_e32 v226, v224, v226
	v_add_u32_e32 v227, 1, v223
	v_and_b32_e32 v227, 3, v227
	v_sub_u32_e32 v226, v226, v227
	v_subrev_u32_e32 v226, 24, v226
	v_cmp_gt_u32_e64 s[42:43], 31, v226
	s_nop 1
	v_cndmask_b32_e64 v227, 0, v226, s[42:43]
	v_mad_u32_u24 v227, v225, 31, v227
	v_lshlrev_b32_e32 v227, 2, v227
	global_load_dword v41, v227, s[38:39]
	v_add_u32_e32 v222, 1024, v0
	v_mul_lo_u32 v223, v222, s36
	v_lshrrev_b32_e32 v223, 26, v223
	v_mul_u32_u24_e32 v224, 1260, v223
	v_sub_u32_e32 v224, v222, v224
	v_mul_u32_u24_e32 v225, 49933, v224
	v_lshrrev_b32_e32 v225, 22, v225
	v_mul_u32_u24_e32 v226, 84, v225
	v_sub_u32_e32 v226, v224, v226
	v_add_u32_e32 v227, 1, v223
	v_and_b32_e32 v227, 3, v227
	v_sub_u32_e32 v226, v226, v227
	v_subrev_u32_e32 v226, 24, v226
	v_cmp_gt_u32_e64 s[44:45], 31, v226
	s_nop 1
	v_cndmask_b32_e64 v227, 0, v226, s[44:45]
	v_mad_u32_u24 v227, v225, 31, v227
	v_lshlrev_b32_e32 v227, 2, v227
	global_load_dword v42, v227, s[38:39]
	v_add_u32_e32 v222, 1536, v0
	v_mul_lo_u32 v223, v222, s36
	v_lshrrev_b32_e32 v223, 26, v223
	v_mul_u32_u24_e32 v224, 1260, v223
	v_sub_u32_e32 v224, v222, v224
	v_mul_u32_u24_e32 v225, 49933, v224
	v_lshrrev_b32_e32 v225, 22, v225
	v_mul_u32_u24_e32 v226, 84, v225
	v_sub_u32_e32 v226, v224, v226
	v_add_u32_e32 v227, 1, v223
	v_and_b32_e32 v227, 3, v227
	v_sub_u32_e32 v226, v226, v227
	v_subrev_u32_e32 v226, 24, v226
	v_cmp_gt_u32_e64 s[46:47], 31, v226
	s_nop 1
	v_cndmask_b32_e64 v227, 0, v226, s[46:47]
	v_mad_u32_u24 v227, v225, 31, v227
	v_lshlrev_b32_e32 v227, 2, v227
	global_load_dword v43, v227, s[38:39]
	v_add_u32_e32 v222, 2048, v0
	v_mul_lo_u32 v223, v222, s36
	v_lshrrev_b32_e32 v223, 26, v223
	v_mul_u32_u24_e32 v224, 1260, v223
	v_sub_u32_e32 v224, v222, v224
	v_mul_u32_u24_e32 v225, 49933, v224
	v_lshrrev_b32_e32 v225, 22, v225
	v_mul_u32_u24_e32 v226, 84, v225
	v_sub_u32_e32 v226, v224, v226
	v_add_u32_e32 v227, 1, v223
	v_and_b32_e32 v227, 3, v227
	v_sub_u32_e32 v226, v226, v227
	v_subrev_u32_e32 v226, 24, v226
	v_cmp_gt_u32_e64 s[48:49], 31, v226
	s_nop 1
	v_cndmask_b32_e64 v227, 0, v226, s[48:49]
	v_mad_u32_u24 v227, v225, 31, v227
	v_lshlrev_b32_e32 v227, 2, v227
	global_load_dword v44, v227, s[38:39]
	v_add_u32_e32 v222, 2560, v0
	v_mul_lo_u32 v223, v222, s36
	v_lshrrev_b32_e32 v223, 26, v223
	v_mul_u32_u24_e32 v224, 1260, v223
	v_sub_u32_e32 v224, v222, v224
	v_mul_u32_u24_e32 v225, 49933, v224
	v_lshrrev_b32_e32 v225, 22, v225
	v_mul_u32_u24_e32 v226, 84, v225
	v_sub_u32_e32 v226, v224, v226
	v_add_u32_e32 v227, 1, v223
	v_and_b32_e32 v227, 3, v227
	v_sub_u32_e32 v226, v226, v227
	v_subrev_u32_e32 v226, 24, v226
	v_cmp_gt_u32_e64 s[50:51], 31, v226
	s_nop 1
	v_cndmask_b32_e64 v227, 0, v226, s[50:51]
	v_mad_u32_u24 v227, v225, 31, v227
	v_lshlrev_b32_e32 v227, 2, v227
	global_load_dword v45, v227, s[38:39]
	v_add_u32_e32 v222, 3072, v0
	v_mul_lo_u32 v223, v222, s36
	v_lshrrev_b32_e32 v223, 26, v223
	v_mul_u32_u24_e32 v224, 1260, v223
	v_sub_u32_e32 v224, v222, v224
	v_mul_u32_u24_e32 v225, 49933, v224
	v_lshrrev_b32_e32 v225, 22, v225
	v_mul_u32_u24_e32 v226, 84, v225
	v_sub_u32_e32 v226, v224, v226
	v_add_u32_e32 v227, 1, v223
	v_and_b32_e32 v227, 3, v227
	v_sub_u32_e32 v226, v226, v227
	v_subrev_u32_e32 v226, 24, v226
	v_cmp_gt_u32_e64 s[52:53], 31, v226
	s_nop 1
	v_cndmask_b32_e64 v227, 0, v226, s[52:53]
	v_mad_u32_u24 v227, v225, 31, v227
	v_lshlrev_b32_e32 v227, 2, v227
	global_load_dword v46, v227, s[38:39]
	v_add_u32_e32 v222, 3584, v0
	v_mul_lo_u32 v223, v222, s36
	v_lshrrev_b32_e32 v223, 26, v223
	v_mul_u32_u24_e32 v224, 1260, v223
	v_sub_u32_e32 v224, v222, v224
	v_mul_u32_u24_e32 v225, 49933, v224
	v_lshrrev_b32_e32 v225, 22, v225
	v_mul_u32_u24_e32 v226, 84, v225
	v_sub_u32_e32 v226, v224, v226
	v_add_u32_e32 v227, 1, v223
	v_and_b32_e32 v227, 3, v227
	v_sub_u32_e32 v226, v226, v227
	v_subrev_u32_e32 v226, 24, v226
	v_cmp_gt_u32_e64 s[54:55], 31, v226
	s_nop 1
	v_cndmask_b32_e64 v227, 0, v226, s[54:55]
	v_mad_u32_u24 v227, v225, 31, v227
	v_lshlrev_b32_e32 v227, 2, v227
	global_load_dword v47, v227, s[38:39]
	v_add_u32_e32 v222, 4096, v0
	v_mul_lo_u32 v223, v222, s36
	v_lshrrev_b32_e32 v223, 26, v223
	v_mul_u32_u24_e32 v224, 1260, v223
	v_sub_u32_e32 v224, v222, v224
	v_mul_u32_u24_e32 v225, 49933, v224
	v_lshrrev_b32_e32 v225, 22, v225
	v_mul_u32_u24_e32 v226, 84, v225
	v_sub_u32_e32 v226, v224, v226
	v_add_u32_e32 v227, 1, v223
	v_and_b32_e32 v227, 3, v227
	v_sub_u32_e32 v226, v226, v227
	v_subrev_u32_e32 v226, 24, v226
	v_cmp_gt_u32_e64 s[56:57], 31, v226
	s_nop 1
	v_cndmask_b32_e64 v227, 0, v226, s[56:57]
	v_mad_u32_u24 v227, v225, 31, v227
	v_lshlrev_b32_e32 v227, 2, v227
	global_load_dword v48, v227, s[38:39]
	v_add_u32_e32 v222, 4608, v0
	v_mul_lo_u32 v223, v222, s36
	v_lshrrev_b32_e32 v223, 26, v223
	v_mul_u32_u24_e32 v224, 1260, v223
	v_sub_u32_e32 v224, v222, v224
	v_mul_u32_u24_e32 v225, 49933, v224
	v_lshrrev_b32_e32 v225, 22, v225
	v_mul_u32_u24_e32 v226, 84, v225
	v_sub_u32_e32 v226, v224, v226
	v_add_u32_e32 v227, 1, v223
	v_and_b32_e32 v227, 3, v227
	v_sub_u32_e32 v226, v226, v227
	v_subrev_u32_e32 v226, 24, v226
	v_cmp_gt_u32_e64 s[58:59], 31, v226
	s_nop 1
	v_cndmask_b32_e64 v227, 0, v226, s[58:59]
	v_mad_u32_u24 v227, v225, 31, v227
	v_lshlrev_b32_e32 v227, 2, v227
	global_load_dword v49, v227, s[38:39]
	v_lshlrev_b32_e32 v222, 2, v0
	s_waitcnt vmcnt(0)
	v_mul_f32_e32 v40, 0x3fb8aa3b, v40
	v_cndmask_b32_e64 v40, 0, v40, s[40:41]
	v_mul_f32_e32 v41, 0x3fb8aa3b, v41
	v_cndmask_b32_e64 v41, 0, v41, s[42:43]
	v_mul_f32_e32 v42, 0x3fb8aa3b, v42
	v_cndmask_b32_e64 v42, 0, v42, s[44:45]
	v_mul_f32_e32 v43, 0x3fb8aa3b, v43
	v_cndmask_b32_e64 v43, 0, v43, s[46:47]
	v_mul_f32_e32 v44, 0x3fb8aa3b, v44
	v_cndmask_b32_e64 v44, 0, v44, s[48:49]
	v_mul_f32_e32 v45, 0x3fb8aa3b, v45
	v_cndmask_b32_e64 v45, 0, v45, s[50:51]
	v_mul_f32_e32 v46, 0x3fb8aa3b, v46
	v_cndmask_b32_e64 v46, 0, v46, s[52:53]
	v_mul_f32_e32 v47, 0x3fb8aa3b, v47
	v_cndmask_b32_e64 v47, 0, v47, s[54:55]
	v_mul_f32_e32 v48, 0x3fb8aa3b, v48
	v_cndmask_b32_e64 v48, 0, v48, s[56:57]
	v_mul_f32_e32 v49, 0x3fb8aa3b, v49
	v_cndmask_b32_e64 v49, 0, v49, s[58:59]
	v_cmp_gt_u32_e32 vcc, 432, v0
	ds_write_b32 v222, v40 offset:35840
	ds_write_b32 v222, v41 offset:37888
	ds_write_b32 v222, v42 offset:39936
	ds_write_b32 v222, v43 offset:41984
	ds_write_b32 v222, v44 offset:44032
	ds_write_b32 v222, v45 offset:46080
	ds_write_b32 v222, v46 offset:48128
	ds_write_b32 v222, v47 offset:50176
	ds_write_b32 v222, v48 offset:52224
	s_and_saveexec_b64 s[60:61], vcc
	ds_write_b32 v222, v49 offset:54272
	s_mov_b64 exec, s[60:61]
	v_mov_b32_e32 v2, 0
	v_mov_b32_e32 v3, 0
	v_mov_b32_e32 v4, 0
	v_mov_b32_e32 v5, 0
	v_mov_b32_e32 v6, 0
	v_mov_b32_e32 v7, 0
	v_mov_b32_e32 v8, 0
	v_mov_b32_e32 v9, 0
	v_mov_b32_e32 v10, 0
	v_mov_b32_e32 v11, 0
	v_mov_b32_e32 v12, 0
	v_mov_b32_e32 v13, 0
	v_mov_b32_e32 v14, 0
	v_mov_b32_e32 v15, 0
	v_mov_b32_e32 v16, 0
	v_mov_b32_e32 v17, 0
	v_mov_b32_e32 v18, 0
	v_mov_b32_e32 v19, 0
	v_mov_b32_e32 v20, 0
	v_mov_b32_e32 v21, 0
	v_mov_b32_e32 v22, 0
	v_mov_b32_e32 v23, 0
	v_mov_b32_e32 v24, 0
	v_mov_b32_e32 v25, 0
	v_mov_b32_e32 v26, 0
	v_mov_b32_e32 v27, 0
	v_mov_b32_e32 v28, 0
	v_mov_b32_e32 v29, 0
	v_mov_b32_e32 v30, 0
	v_mov_b32_e32 v31, 0
	v_mov_b32_e32 v32, 0
	v_mov_b32_e32 v33, 0
	v_mov_b32_e32 v212, 0
	v_mov_b32_e32 v213, 0
	v_mov_b32_e32 v214, 0
	v_mov_b32_e32 v220, 0xff7fffff
	v_mov_b32_e32 v221, 0
	s_mov_b64 s[26:27], -1
	v_and_b32_e32 v216, 15, v0
	v_bfe_u32 v217, v0, 5, 1
	s_lshl_b32 s36, s11, 4
	v_add_u32_e32 v222, s36, v216
	v_subrev_u32_e32 v223, 8, v222
	v_med3_i32 v223, v223, 0, 48
	v_lshl_add_u32 v224, v217, 2, s66
	v_sub_u32_e32 v224, v224, v223
	v_add_u32_e32 v225, 0, v224
	v_cmp_gt_u32_e32 vcc, 16, v225
	s_nop 1
	v_cndmask_b32_e32 v114, v229, v228, vcc
	v_add_u32_e32 v225, 1, v224
	v_cmp_gt_u32_e32 vcc, 16, v225
	s_nop 1
	v_cndmask_b32_e32 v115, v229, v228, vcc
	v_add_u32_e32 v225, 2, v224
	v_cmp_gt_u32_e32 vcc, 16, v225
	s_nop 1
	v_cndmask_b32_e32 v116, v229, v228, vcc
	v_add_u32_e32 v225, 3, v224
	v_cmp_gt_u32_e32 vcc, 16, v225
	s_nop 1
	v_cndmask_b32_e32 v117, v229, v228, vcc
	v_add_u32_e32 v225, 8, v224
	v_cmp_gt_u32_e32 vcc, 16, v225
	s_nop 1
	v_cndmask_b32_e32 v118, v229, v228, vcc
	v_add_u32_e32 v225, 9, v224
	v_cmp_gt_u32_e32 vcc, 16, v225
	s_nop 1
	v_cndmask_b32_e32 v119, v229, v228, vcc
	v_add_u32_e32 v225, 10, v224
	v_cmp_gt_u32_e32 vcc, 16, v225
	s_nop 1
	v_cndmask_b32_e32 v120, v229, v228, vcc
	v_add_u32_e32 v225, 11, v224
	v_cmp_gt_u32_e32 vcc, 16, v225
	s_nop 1
	v_cndmask_b32_e32 v121, v229, v228, vcc
	v_add_u32_e32 v225, 16, v224
	v_cmp_gt_u32_e32 vcc, 16, v225
	s_nop 1
	v_cndmask_b32_e32 v122, v229, v228, vcc
	v_add_u32_e32 v225, 17, v224
	v_cmp_gt_u32_e32 vcc, 16, v225
	s_nop 1
	v_cndmask_b32_e32 v123, v229, v228, vcc
	v_add_u32_e32 v225, 18, v224
	v_cmp_gt_u32_e32 vcc, 16, v225
	s_nop 1
	v_cndmask_b32_e32 v124, v229, v228, vcc
	v_add_u32_e32 v225, 19, v224
	v_cmp_gt_u32_e32 vcc, 16, v225
	s_nop 1
	v_cndmask_b32_e32 v125, v229, v228, vcc
	v_add_u32_e32 v225, 24, v224
	v_cmp_gt_u32_e32 vcc, 16, v225
	s_nop 1
	v_cndmask_b32_e32 v126, v229, v228, vcc
	v_add_u32_e32 v225, 25, v224
	v_cmp_gt_u32_e32 vcc, 16, v225
	s_nop 1
	v_cndmask_b32_e32 v127, v229, v228, vcc
	v_add_u32_e32 v225, 26, v224
	v_cmp_gt_u32_e32 vcc, 16, v225
	s_nop 1
	v_cndmask_b32_e32 v128, v229, v228, vcc
	v_add_u32_e32 v225, 27, v224
	v_cmp_gt_u32_e32 vcc, 16, v225
	s_nop 1
	v_cndmask_b32_e32 v129, v229, v228, vcc

.Lna_wloop:
	s_sub_i32 s36, s24, s23
	s_cmp_lt_u32 s36, s63
	s_cselect_b64 s[40:41], -1, 0
	s_add_i32 s36, s36, 1
	s_cmp_lt_u32 s36, 8
	s_cselect_b64 s[44:45], -1, 0
	s_sub_i32 s37, s36, s62
	s_cmp_lt_u32 s37, 8
	s_cselect_b64 s[46:47], -1, 0
	s_and_b64 s[48:49], s[44:45], s[64:65]
	s_andn2_b64 s[38:39], s[46:47], s[64:65]
	s_or_b64 s[48:49], s[48:49], s[38:39]
	s_or_b64 s[42:43], s[44:45], s[46:47]
	s_and_b64 s[44:45], s[44:45], s[46:47]
	s_and_b64 s[44:45], s[44:45], s[40:41]
	s_cmp_eq_u64 s[44:45], 0
	s_cbranch_scc1 .Lna_slow_w1
	ds_read_b128 v[146:149], v199 offset:0
	ds_read_b128 v[150:153], v199 offset:32
	ds_read_b128 v[154:157], v199 offset:64
	ds_read_b128 v[158:161], v199 offset:96
	v_add_u32_e32 v210, s25, v208
	v_exp_f32_e32 v66, v66
	v_exp_f32_e32 v67, v67
	v_exp_f32_e32 v68, v68
	v_exp_f32_e32 v69, v69
	v_add_f32_e32 v213, v213, v66
	v_add_f32_e32 v214, v214, v67
	s_waitcnt lgkmcnt(3)
	v_mfma_f32_32x32x16_bf16 v[34:49], v[146:149], v[98:101], v[114:129]
	ds_read_b64 v[162:163], v201 offset:8704
	ds_read_b64 v[164:165], v201 offset:8720
	v_add_f32_e32 v213, v213, v68
	v_add_f32_e32 v214, v214, v69
	v_exp_f32_e32 v70, v70
	v_exp_f32_e32 v71, v71
	v_exp_f32_e32 v72, v72
	v_exp_f32_e32 v73, v73
	s_waitcnt lgkmcnt(4)
	v_mfma_f32_32x32x16_bf16 v[34:49], v[150:153], v[102:105], v[34:49]
	ds_read_b64 v[166:167], v201 offset:13056
	ds_read_b64 v[168:169], v201 offset:13072
	v_add_f32_e32 v213, v213, v70
	v_add_f32_e32 v214, v214, v71
	v_add_f32_e32 v213, v213, v72
	v_add_f32_e32 v214, v214, v73
	v_cvt_pk_bf16_f32 v66, v66, v67
	v_cvt_pk_bf16_f32 v67, v68, v69
	v_cvt_pk_bf16_f32 v68, v70, v71
	v_cvt_pk_bf16_f32 v69, v72, v73
	v_exp_f32_e32 v74, v74
	s_waitcnt lgkmcnt(5)
	v_mfma_f32_32x32x16_bf16 v[34:49], v[154:157], v[106:109], v[34:49]
	ds_read_b64 v[170:171], v201 offset:8736
	ds_read_b64 v[172:173], v201 offset:8752
	v_exp_f32_e32 v75, v75
	v_exp_f32_e32 v76, v76
	v_exp_f32_e32 v77, v77
	v_add_f32_e32 v213, v213, v74
	v_add_f32_e32 v214, v214, v75
	v_add_f32_e32 v213, v213, v76
	s_waitcnt lgkmcnt(6)
	v_mfma_f32_32x32x16_bf16 v[34:49], v[158:161], v[110:113], v[34:49]
	ds_read_b64 v[174:175], v201 offset:13088
	ds_read_b64 v[176:177], v201 offset:13104
	ds_read_b128 v[146:149], v210 offset:0
	ds_read_b128 v[150:153], v210 offset:32
	ds_read_b128 v[154:157], v210 offset:64
	ds_read_b128 v[158:161], v210 offset:96
	v_add_f32_e32 v214, v214, v77
	v_exp_f32_e32 v78, v78
	v_exp_f32_e32 v79, v79
	v_exp_f32_e32 v80, v80
	v_exp_f32_e32 v81, v81
	s_waitcnt lgkmcnt(10)
	v_mfma_f32_32x32x16_bf16 v[2:17], v[162:165], v[66:69], v[2:17]
	v_add_f32_e32 v213, v213, v78
	v_add_f32_e32 v214, v214, v79
	v_add_f32_e32 v213, v213, v80
	v_add_f32_e32 v214, v214, v81
	v_cvt_pk_bf16_f32 v74, v74, v75
	v_cvt_pk_bf16_f32 v75, v76, v77
	v_cvt_pk_bf16_f32 v76, v78, v79
	v_cvt_pk_bf16_f32 v77, v80, v81
	s_waitcnt lgkmcnt(8)
	v_mfma_f32_32x32x16_bf16 v[18:33], v[166:169], v[66:69], v[18:33]
	s_waitcnt lgkmcnt(0)
	v_add_f32_e32 v34, v34, v146
	v_add_f32_e32 v35, v35, v147
	v_add_f32_e32 v36, v36, v148
	v_add_f32_e32 v37, v37, v149
	v_add_f32_e32 v38, v38, v150
	v_add_f32_e32 v39, v39, v151
	v_add_f32_e32 v40, v40, v152
	v_add_f32_e32 v41, v41, v153
	v_add_f32_e32 v42, v42, v154
	v_add_f32_e32 v43, v43, v155
	v_add_f32_e32 v44, v44, v156
	v_mfma_f32_32x32x16_bf16 v[2:17], v[170:173], v[74:77], v[2:17]
	v_add_f32_e32 v45, v45, v157
	v_add_f32_e32 v46, v46, v158
	v_add_f32_e32 v47, v47, v159
	v_add_f32_e32 v48, v48, v160
	v_add_f32_e32 v49, v49, v161
	v_max3_f32 v216, v34, v35, v36
	v_max3_f32 v217, v42, v43, v44
	v_max3_f32 v216, v216, v37, v38
	v_max3_f32 v217, v217, v45, v46
	v_max3_f32 v216, v216, v39, v40
	v_mfma_f32_32x32x16_bf16 v[18:33], v[174:177], v[74:77], v[18:33]
	s_waitcnt vmcnt(2)
	ds_write_b128 v204, v[230:233] offset:9216
	ds_write_b64 v205, v[234:235] offset:0
	ds_write_b64 v205, v[236:237] offset:8
	global_load_dwordx4 v[230:233], v206, s[12:13]
	s_add_i32 s20, s20, 1
	s_add_u32 s12, s12, 0x2000
	s_addc_u32 s13, s13, 0
	s_cmp_eq_u32 s20, s22
	s_cselect_b32 s12, s16, s12
	s_cselect_b32 s13, s17, s13
	global_load_dwordx4 v[234:237], v207, s[14:15]
	s_add_i32 s21, s21, 1
	s_add_u32 s14, s14, 0x80
	s_addc_u32 s15, s15, 0
	s_cmp_eq_u32 s21, s22
	s_cselect_b32 s14, s18, s14
	s_cselect_b32 s15, s19, s15
	v_max3_f32 v217, v217, v47, v48
	v_max_f32_e32 v216, v216, v41
	v_max_f32_e32 v217, v217, v49
	v_max_f32_e32 v216, v216, v217
	v_mov_b32_e32 v217, v216
	s_nop 1
	v_permlane32_swap_b32_e32 v216, v217
	v_max_f32_e32 v215, v216, v217
	v_cmp_lt_f32_e32 vcc, 4.0, v215
	s_or_b64 s[28:29], vcc, s[26:27]
	s_cmp_lg_u64 s[28:29], 0
	s_cbranch_scc0 .Lna_nr_w1f
	s_nop 15
	v_max_f32_e32 v216, v215, v220
	v_cmp_lt_f32_e32 vcc, 0xf0c9f2ca, v215
	s_nop 1
	v_cndmask_b32_e32 v216, 0, v216, vcc
	v_exp_f32_e64 v217, -v216
	v_add_f32_e32 v212, v212, v216
	v_and_b32_e32 v217, v217, v221
	v_sub_f32_e32 v34, v34, v216
	v_sub_f32_e32 v35, v35, v216
	v_sub_f32_e32 v36, v36, v216
	v_sub_f32_e32 v37, v37, v216
	v_sub_f32_e32 v38, v38, v216
	v_sub_f32_e32 v39, v39, v216
	v_sub_f32_e32 v40, v40, v216
	v_sub_f32_e32 v41, v41, v216
	v_sub_f32_e32 v42, v42, v216
	v_sub_f32_e32 v43, v43, v216
	v_sub_f32_e32 v44, v44, v216
	v_sub_f32_e32 v45, v45, v216
	v_sub_f32_e32 v46, v46, v216
	v_sub_f32_e32 v47, v47, v216
	v_sub_f32_e32 v48, v48, v216
	v_sub_f32_e32 v49, v49, v216
	v_sub_f32_e32 v114, v114, v216
	v_sub_f32_e32 v115, v115, v216
	v_sub_f32_e32 v116, v116, v216
	v_sub_f32_e32 v117, v117, v216
	v_sub_f32_e32 v118, v118, v216
	v_sub_f32_e32 v119, v119, v216
	v_sub_f32_e32 v120, v120, v216
	v_sub_f32_e32 v121, v121, v216
	v_sub_f32_e32 v122, v122, v216
	v_sub_f32_e32 v123, v123, v216
	v_sub_f32_e32 v124, v124, v216
	v_sub_f32_e32 v125, v125, v216
	v_sub_f32_e32 v126, v126, v216
	v_sub_f32_e32 v127, v127, v216
	v_sub_f32_e32 v128, v128, v216
	v_sub_f32_e32 v129, v129, v216
	v_mul_f32_e32 v213, v213, v217
	v_mul_f32_e32 v214, v214, v217
	v_mul_f32_e32 v2, v2, v217
	v_mul_f32_e32 v3, v3, v217
	v_mul_f32_e32 v4, v4, v217
	v_mul_f32_e32 v5, v5, v217
	v_mul_f32_e32 v6, v6, v217
	v_mul_f32_e32 v7, v7, v217
	v_mul_f32_e32 v8, v8, v217
	v_mul_f32_e32 v9, v9, v217
	v_mul_f32_e32 v10, v10, v217
	v_mul_f32_e32 v11, v11, v217
	v_mul_f32_e32 v12, v12, v217
	v_mul_f32_e32 v13, v13, v217
	v_mul_f32_e32 v14, v14, v217
	v_mul_f32_e32 v15, v15, v217
	v_mul_f32_e32 v16, v16, v217
	v_mul_f32_e32 v17, v17, v217
	v_mul_f32_e32 v18, v18, v217
	v_mul_f32_e32 v19, v19, v217
	v_mul_f32_e32 v20, v20, v217
	v_mul_f32_e32 v21, v21, v217
	v_mul_f32_e32 v22, v22, v217
	v_mul_f32_e32 v23, v23, v217
	v_mul_f32_e32 v24, v24, v217
	v_mul_f32_e32 v25, v25, v217
	v_mul_f32_e32 v26, v26, v217
	v_mul_f32_e32 v27, v27, v217
	v_mul_f32_e32 v28, v28, v217
	v_mul_f32_e32 v29, v29, v217
	v_mul_f32_e32 v30, v30, v217
	v_mul_f32_e32 v31, v31, v217
	v_mul_f32_e32 v32, v32, v217
	v_mul_f32_e32 v33, v33, v217
	v_cndmask_b32_e32 v220, v220, v228, vcc
	v_cndmask_b32_e64 v221, v221, -1, vcc
	s_andn2_b64 s[26:27], s[26:27], vcc

.Lna_slow_w1:
	s_cmp_eq_u64 s[40:41], 0
	s_cbranch_scc1 .Lna_sl_a_w1s
	ds_read_b64 v[162:163], v201 offset:8704
	ds_read_b64 v[164:165], v201 offset:8720
	ds_read_b64 v[166:167], v201 offset:13056
	ds_read_b64 v[168:169], v201 offset:13072
	ds_read_b64 v[170:171], v201 offset:8736
	ds_read_b64 v[172:173], v201 offset:8752
	ds_read_b64 v[174:175], v201 offset:13088
	ds_read_b64 v[176:177], v201 offset:13104
	v_exp_f32_e32 v66, v66
	v_exp_f32_e32 v67, v67
	v_exp_f32_e32 v68, v68
	v_exp_f32_e32 v69, v69
	v_add_f32_e32 v213, v213, v66
	v_add_f32_e32 v214, v214, v67
	v_add_f32_e32 v213, v213, v68
	v_add_f32_e32 v214, v214, v69
	v_exp_f32_e32 v70, v70
	v_exp_f32_e32 v71, v71
	v_exp_f32_e32 v72, v72
	v_exp_f32_e32 v73, v73
	v_add_f32_e32 v213, v213, v70
	v_add_f32_e32 v214, v214, v71
	v_add_f32_e32 v213, v213, v72
	v_add_f32_e32 v214, v214, v73
	v_cvt_pk_bf16_f32 v66, v66, v67
	v_cvt_pk_bf16_f32 v67, v68, v69
	v_cvt_pk_bf16_f32 v68, v70, v71
	v_cvt_pk_bf16_f32 v69, v72, v73
	v_exp_f32_e32 v74, v74
	v_exp_f32_e32 v75, v75
	v_exp_f32_e32 v76, v76
	v_exp_f32_e32 v77, v77
	v_add_f32_e32 v213, v213, v74
	v_add_f32_e32 v214, v214, v75
	v_add_f32_e32 v213, v213, v76
	v_add_f32_e32 v214, v214, v77
	v_exp_f32_e32 v78, v78
	v_exp_f32_e32 v79, v79
	v_exp_f32_e32 v80, v80
	v_exp_f32_e32 v81, v81
	v_add_f32_e32 v213, v213, v78
	v_add_f32_e32 v214, v214, v79
	v_add_f32_e32 v213, v213, v80
	v_add_f32_e32 v214, v214, v81
	v_cvt_pk_bf16_f32 v74, v74, v75
	v_cvt_pk_bf16_f32 v75, v76, v77
	v_cvt_pk_bf16_f32 v76, v78, v79
	v_cvt_pk_bf16_f32 v77, v80, v81
	s_nop 1
	s_waitcnt lgkmcnt(6)
	v_mfma_f32_32x32x16_bf16 v[2:17], v[162:165], v[66:69], v[2:17]
	s_waitcnt lgkmcnt(4)
	v_mfma_f32_32x32x16_bf16 v[18:33], v[166:169], v[66:69], v[18:33]
	s_waitcnt lgkmcnt(2)
	v_mfma_f32_32x32x16_bf16 v[2:17], v[170:173], v[74:77], v[2:17]
	s_waitcnt lgkmcnt(0)
	v_mfma_f32_32x32x16_bf16 v[18:33], v[174:177], v[74:77], v[18:33]
.Lna_sl_a_w1s:
	s_waitcnt lgkmcnt(0)
	s_cmp_eq_u64 s[42:43], 0
	s_cbranch_scc1 .Lna_sl_b_w1s
	ds_read_b128 v[146:149], v199 offset:0
	ds_read_b128 v[150:153], v199 offset:32
	ds_read_b128 v[154:157], v199 offset:64
	ds_read_b128 v[158:161], v199 offset:96
	s_waitcnt lgkmcnt(3)
	v_mfma_f32_32x32x16_bf16 v[34:49], v[146:149], v[98:101], v[114:129]
	s_waitcnt lgkmcnt(2)
	v_mfma_f32_32x32x16_bf16 v[34:49], v[150:153], v[102:105], v[34:49]
	s_waitcnt lgkmcnt(1)
	v_mfma_f32_32x32x16_bf16 v[34:49], v[154:157], v[106:109], v[34:49]
	s_waitcnt lgkmcnt(0)
	v_mfma_f32_32x32x16_bf16 v[34:49], v[158:161], v[110:113], v[34:49]
	v_add_u32_e32 v210, s25, v208
	ds_read_b128 v[146:149], v210 offset:0
	ds_read_b128 v[150:153], v210 offset:32
	ds_read_b128 v[154:157], v210 offset:64
	ds_read_b128 v[158:161], v210 offset:96
	s_waitcnt lgkmcnt(0)
	s_nop 15
	v_add_f32_e32 v34, v34, v146
	v_add_f32_e32 v35, v35, v147
	v_add_f32_e32 v36, v36, v148
	v_add_f32_e32 v37, v37, v149
	v_add_f32_e32 v38, v38, v150
	v_add_f32_e32 v39, v39, v151
	v_add_f32_e32 v40, v40, v152
	v_add_f32_e32 v41, v41, v153
	v_add_f32_e32 v42, v42, v154
	v_add_f32_e32 v43, v43, v155
	v_add_f32_e32 v44, v44, v156
	v_add_f32_e32 v45, v45, v157
	v_add_f32_e32 v46, v46, v158
	v_add_f32_e32 v47, v47, v159
	v_add_f32_e32 v48, v48, v160
	v_add_f32_e32 v49, v49, v161
	v_cndmask_b32_e64 v34, v229, v34, s[48:49]
	v_cndmask_b32_e64 v35, v229, v35, s[48:49]
	v_cndmask_b32_e64 v36, v229, v36, s[48:49]
	v_cndmask_b32_e64 v37, v229, v37, s[48:49]
	v_cndmask_b32_e64 v38, v229, v38, s[48:49]
	v_cndmask_b32_e64 v39, v229, v39, s[48:49]
	v_cndmask_b32_e64 v40, v229, v40, s[48:49]
	v_cndmask_b32_e64 v41, v229, v41, s[48:49]
	v_cndmask_b32_e64 v42, v229, v42, s[48:49]
	v_cndmask_b32_e64 v43, v229, v43, s[48:49]
	v_cndmask_b32_e64 v44, v229, v44, s[48:49]
	v_cndmask_b32_e64 v45, v229, v45, s[48:49]
	v_cndmask_b32_e64 v46, v229, v46, s[48:49]
	v_cndmask_b32_e64 v47, v229, v47, s[48:49]
	v_cndmask_b32_e64 v48, v229, v48, s[48:49]
	v_cndmask_b32_e64 v49, v229, v49, s[48:49]
	v_max3_f32 v216, v34, v35, v36
	v_max3_f32 v217, v42, v43, v44
	v_max3_f32 v216, v216, v37, v38
	v_max3_f32 v217, v217, v45, v46
	v_max3_f32 v216, v216, v39, v40
	v_max3_f32 v217, v217, v47, v48
	v_max_f32_e32 v216, v216, v41
	v_max_f32_e32 v217, v217, v49
	v_max_f32_e32 v216, v216, v217
	v_mov_b32_e32 v217, v216
	s_nop 1
	v_permlane32_swap_b32_e32 v216, v217
	v_max_f32_e32 v215, v216, v217
	v_cmp_lt_f32_e32 vcc, 4.0, v215
	s_or_b64 s[28:29], vcc, s[26:27]
	s_cmp_lg_u64 s[28:29], 0
	s_cbranch_scc0 .Lna_nr_w1s
	s_nop 15
	v_max_f32_e32 v216, v215, v220
	v_cmp_lt_f32_e32 vcc, 0xf0c9f2ca, v215
	s_nop 1
	v_cndmask_b32_e32 v216, 0, v216, vcc
	v_exp_f32_e64 v217, -v216
	v_add_f32_e32 v212, v212, v216
	v_and_b32_e32 v217, v217, v221
	v_sub_f32_e32 v34, v34, v216
	v_sub_f32_e32 v35, v35, v216
	v_sub_f32_e32 v36, v36, v216
	v_sub_f32_e32 v37, v37, v216
	v_sub_f32_e32 v38, v38, v216
	v_sub_f32_e32 v39, v39, v216
	v_sub_f32_e32 v40, v40, v216
	v_sub_f32_e32 v41, v41, v216
	v_sub_f32_e32 v42, v42, v216
	v_sub_f32_e32 v43, v43, v216
	v_sub_f32_e32 v44, v44, v216
	v_sub_f32_e32 v45, v45, v216
	v_sub_f32_e32 v46, v46, v216
	v_sub_f32_e32 v47, v47, v216
	v_sub_f32_e32 v48, v48, v216
	v_sub_f32_e32 v49, v49, v216
	v_sub_f32_e32 v114, v114, v216
	v_sub_f32_e32 v115, v115, v216
	v_sub_f32_e32 v116, v116, v216
	v_sub_f32_e32 v117, v117, v216
	v_sub_f32_e32 v118, v118, v216
	v_sub_f32_e32 v119, v119, v216
	v_sub_f32_e32 v120, v120, v216
	v_sub_f32_e32 v121, v121, v216
	v_sub_f32_e32 v122, v122, v216
	v_sub_f32_e32 v123, v123, v216
	v_sub_f32_e32 v124, v124, v216
	v_sub_f32_e32 v125, v125, v216
	v_sub_f32_e32 v126, v126, v216
	v_sub_f32_e32 v127, v127, v216
	v_sub_f32_e32 v128, v128, v216
	v_sub_f32_e32 v129, v129, v216
	v_mul_f32_e32 v213, v213, v217
	v_mul_f32_e32 v214, v214, v217
	v_mul_f32_e32 v2, v2, v217
	v_mul_f32_e32 v3, v3, v217
	v_mul_f32_e32 v4, v4, v217
	v_mul_f32_e32 v5, v5, v217
	v_mul_f32_e32 v6, v6, v217
	v_mul_f32_e32 v7, v7, v217
	v_mul_f32_e32 v8, v8, v217
	v_mul_f32_e32 v9, v9, v217
	v_mul_f32_e32 v10, v10, v217
	v_mul_f32_e32 v11, v11, v217
	v_mul_f32_e32 v12, v12, v217
	v_mul_f32_e32 v13, v13, v217
	v_mul_f32_e32 v14, v14, v217
	v_mul_f32_e32 v15, v15, v217
	v_mul_f32_e32 v16, v16, v217
	v_mul_f32_e32 v17, v17, v217
	v_mul_f32_e32 v18, v18, v217
	v_mul_f32_e32 v19, v19, v217
	v_mul_f32_e32 v20, v20, v217
	v_mul_f32_e32 v21, v21, v217
	v_mul_f32_e32 v22, v22, v217
	v_mul_f32_e32 v23, v23, v217
	v_mul_f32_e32 v24, v24, v217
	v_mul_f32_e32 v25, v25, v217
	v_mul_f32_e32 v26, v26, v217
	v_mul_f32_e32 v27, v27, v217
	v_mul_f32_e32 v28, v28, v217
	v_mul_f32_e32 v29, v29, v217
	v_mul_f32_e32 v30, v30, v217
	v_mul_f32_e32 v31, v31, v217
	v_mul_f32_e32 v32, v32, v217
	v_mul_f32_e32 v33, v33, v217
	v_cndmask_b32_e32 v220, v220, v228, vcc
	v_cndmask_b32_e64 v221, v221, -1, vcc
	s_andn2_b64 s[26:27], s[26:27], vcc

.Lna_done_w1:
	s_add_i32 s24, s24, 1
	s_add_i32 s25, s25, 0x150
	s_sub_i32 s36, s24, s23
	s_cmp_lt_u32 s36, s63
	s_cselect_b64 s[40:41], -1, 0
	s_add_i32 s36, s36, 1
	s_cmp_lt_u32 s36, 8
	s_cselect_b64 s[44:45], -1, 0
	s_sub_i32 s37, s36, s62
	s_cmp_lt_u32 s37, 8
	s_cselect_b64 s[46:47], -1, 0
	s_and_b64 s[48:49], s[44:45], s[64:65]
	s_andn2_b64 s[38:39], s[46:47], s[64:65]
	s_or_b64 s[48:49], s[48:49], s[38:39]
	s_or_b64 s[42:43], s[44:45], s[46:47]
	s_and_b64 s[44:45], s[44:45], s[46:47]
	s_and_b64 s[44:45], s[44:45], s[40:41]
	s_cmp_eq_u64 s[44:45], 0
	s_cbranch_scc1 .Lna_slow_w0
	ds_read_b128 v[146:149], v199 offset:9216
	ds_read_b128 v[150:153], v199 offset:9248
	ds_read_b128 v[154:157], v199 offset:9280
	ds_read_b128 v[158:161], v199 offset:9312
	v_add_u32_e32 v210, s25, v208
	v_exp_f32_e32 v34, v34
	v_exp_f32_e32 v35, v35
	v_exp_f32_e32 v36, v36
	v_exp_f32_e32 v37, v37
	v_add_f32_e32 v213, v213, v34
	v_add_f32_e32 v214, v214, v35
	s_waitcnt lgkmcnt(3)
	v_mfma_f32_32x32x16_bf16 v[66:81], v[146:149], v[98:101], v[114:129]
	ds_read_b64 v[162:163], v201 offset:0
	ds_read_b64 v[164:165], v201 offset:16
	v_add_f32_e32 v213, v213, v36
	v_add_f32_e32 v214, v214, v37
	v_exp_f32_e32 v38, v38
	v_exp_f32_e32 v39, v39
	v_exp_f32_e32 v40, v40
	v_exp_f32_e32 v41, v41
	s_waitcnt lgkmcnt(4)
	v_mfma_f32_32x32x16_bf16 v[66:81], v[150:153], v[102:105], v[66:81]
	ds_read_b64 v[166:167], v201 offset:4352
	ds_read_b64 v[168:169], v201 offset:4368
	v_add_f32_e32 v213, v213, v38
	v_add_f32_e32 v214, v214, v39
	v_add_f32_e32 v213, v213, v40
	v_add_f32_e32 v214, v214, v41
	v_cvt_pk_bf16_f32 v34, v34, v35
	v_cvt_pk_bf16_f32 v35, v36, v37
	v_cvt_pk_bf16_f32 v36, v38, v39
	v_cvt_pk_bf16_f32 v37, v40, v41
	v_exp_f32_e32 v42, v42
	s_waitcnt lgkmcnt(5)
	v_mfma_f32_32x32x16_bf16 v[66:81], v[154:157], v[106:109], v[66:81]
	ds_read_b64 v[170:171], v201 offset:32
	ds_read_b64 v[172:173], v201 offset:48
	v_exp_f32_e32 v43, v43
	v_exp_f32_e32 v44, v44
	v_exp_f32_e32 v45, v45
	v_add_f32_e32 v213, v213, v42
	v_add_f32_e32 v214, v214, v43
	v_add_f32_e32 v213, v213, v44
	s_waitcnt lgkmcnt(6)
	v_mfma_f32_32x32x16_bf16 v[66:81], v[158:161], v[110:113], v[66:81]
	ds_read_b64 v[174:175], v201 offset:4384
	ds_read_b64 v[176:177], v201 offset:4400
	ds_read_b128 v[146:149], v210 offset:0
	ds_read_b128 v[150:153], v210 offset:32
	ds_read_b128 v[154:157], v210 offset:64
	ds_read_b128 v[158:161], v210 offset:96
	v_add_f32_e32 v214, v214, v45
	v_exp_f32_e32 v46, v46
	v_exp_f32_e32 v47, v47
	v_exp_f32_e32 v48, v48
	v_exp_f32_e32 v49, v49
	s_waitcnt lgkmcnt(10)
	v_mfma_f32_32x32x16_bf16 v[2:17], v[162:165], v[34:37], v[2:17]
	v_add_f32_e32 v213, v213, v46
	v_add_f32_e32 v214, v214, v47
	v_add_f32_e32 v213, v213, v48
	v_add_f32_e32 v214, v214, v49
	v_cvt_pk_bf16_f32 v42, v42, v43
	v_cvt_pk_bf16_f32 v43, v44, v45
	v_cvt_pk_bf16_f32 v44, v46, v47
	v_cvt_pk_bf16_f32 v45, v48, v49
	s_waitcnt lgkmcnt(8)
	v_mfma_f32_32x32x16_bf16 v[18:33], v[166:169], v[34:37], v[18:33]
	s_waitcnt lgkmcnt(0)
	v_add_f32_e32 v66, v66, v146
	v_add_f32_e32 v67, v67, v147
	v_add_f32_e32 v68, v68, v148
	v_add_f32_e32 v69, v69, v149
	v_add_f32_e32 v70, v70, v150
	v_add_f32_e32 v71, v71, v151
	v_add_f32_e32 v72, v72, v152
	v_add_f32_e32 v73, v73, v153
	v_add_f32_e32 v74, v74, v154
	v_add_f32_e32 v75, v75, v155
	v_add_f32_e32 v76, v76, v156
	v_mfma_f32_32x32x16_bf16 v[2:17], v[170:173], v[42:45], v[2:17]
	v_add_f32_e32 v77, v77, v157
	v_add_f32_e32 v78, v78, v158
	v_add_f32_e32 v79, v79, v159
	v_add_f32_e32 v80, v80, v160
	v_add_f32_e32 v81, v81, v161
	v_max3_f32 v216, v66, v67, v68
	v_max3_f32 v217, v74, v75, v76
	v_max3_f32 v216, v216, v69, v70
	v_max3_f32 v217, v217, v77, v78
	v_max3_f32 v216, v216, v71, v72
	v_mfma_f32_32x32x16_bf16 v[18:33], v[174:177], v[42:45], v[18:33]
	s_waitcnt vmcnt(2)
	ds_write_b128 v204, v[188:191] offset:0
	ds_write_b64 v205, v[192:193] offset:8704
	ds_write_b64 v205, v[194:195] offset:8712
	global_load_dwordx4 v[188:191], v206, s[12:13]
	s_add_i32 s20, s20, 1
	s_add_u32 s12, s12, 0x2000
	s_addc_u32 s13, s13, 0
	s_cmp_eq_u32 s20, s22
	s_cselect_b32 s12, s16, s12
	s_cselect_b32 s13, s17, s13
	global_load_dwordx4 v[192:195], v207, s[14:15]
	s_add_i32 s21, s21, 1
	s_add_u32 s14, s14, 0x80
	s_addc_u32 s15, s15, 0
	s_cmp_eq_u32 s21, s22
	s_cselect_b32 s14, s18, s14
	s_cselect_b32 s15, s19, s15
	v_max3_f32 v217, v217, v79, v80
	v_max_f32_e32 v216, v216, v73
	v_max_f32_e32 v217, v217, v81
	v_max_f32_e32 v216, v216, v217
	v_mov_b32_e32 v217, v216
	s_nop 1
	v_permlane32_swap_b32_e32 v216, v217
	v_max_f32_e32 v215, v216, v217
	v_cmp_lt_f32_e32 vcc, 4.0, v215
	s_or_b64 s[28:29], vcc, s[26:27]
	s_cmp_lg_u64 s[28:29], 0
	s_cbranch_scc0 .Lna_nr_w0f
	s_nop 15
	v_max_f32_e32 v216, v215, v220
	v_cmp_lt_f32_e32 vcc, 0xf0c9f2ca, v215
	s_nop 1
	v_cndmask_b32_e32 v216, 0, v216, vcc
	v_exp_f32_e64 v217, -v216
	v_add_f32_e32 v212, v212, v216
	v_and_b32_e32 v217, v217, v221
	v_sub_f32_e32 v66, v66, v216
	v_sub_f32_e32 v67, v67, v216
	v_sub_f32_e32 v68, v68, v216
	v_sub_f32_e32 v69, v69, v216
	v_sub_f32_e32 v70, v70, v216
	v_sub_f32_e32 v71, v71, v216
	v_sub_f32_e32 v72, v72, v216
	v_sub_f32_e32 v73, v73, v216
	v_sub_f32_e32 v74, v74, v216
	v_sub_f32_e32 v75, v75, v216
	v_sub_f32_e32 v76, v76, v216
	v_sub_f32_e32 v77, v77, v216
	v_sub_f32_e32 v78, v78, v216
	v_sub_f32_e32 v79, v79, v216
	v_sub_f32_e32 v80, v80, v216
	v_sub_f32_e32 v81, v81, v216
	v_sub_f32_e32 v114, v114, v216
	v_sub_f32_e32 v115, v115, v216
	v_sub_f32_e32 v116, v116, v216
	v_sub_f32_e32 v117, v117, v216
	v_sub_f32_e32 v118, v118, v216
	v_sub_f32_e32 v119, v119, v216
	v_sub_f32_e32 v120, v120, v216
	v_sub_f32_e32 v121, v121, v216
	v_sub_f32_e32 v122, v122, v216
	v_sub_f32_e32 v123, v123, v216
	v_sub_f32_e32 v124, v124, v216
	v_sub_f32_e32 v125, v125, v216
	v_sub_f32_e32 v126, v126, v216
	v_sub_f32_e32 v127, v127, v216
	v_sub_f32_e32 v128, v128, v216
	v_sub_f32_e32 v129, v129, v216
	v_mul_f32_e32 v213, v213, v217
	v_mul_f32_e32 v214, v214, v217
	v_mul_f32_e32 v2, v2, v217
	v_mul_f32_e32 v3, v3, v217
	v_mul_f32_e32 v4, v4, v217
	v_mul_f32_e32 v5, v5, v217
	v_mul_f32_e32 v6, v6, v217
	v_mul_f32_e32 v7, v7, v217
	v_mul_f32_e32 v8, v8, v217
	v_mul_f32_e32 v9, v9, v217
	v_mul_f32_e32 v10, v10, v217
	v_mul_f32_e32 v11, v11, v217
	v_mul_f32_e32 v12, v12, v217
	v_mul_f32_e32 v13, v13, v217
	v_mul_f32_e32 v14, v14, v217
	v_mul_f32_e32 v15, v15, v217
	v_mul_f32_e32 v16, v16, v217
	v_mul_f32_e32 v17, v17, v217
	v_mul_f32_e32 v18, v18, v217
	v_mul_f32_e32 v19, v19, v217
	v_mul_f32_e32 v20, v20, v217
	v_mul_f32_e32 v21, v21, v217
	v_mul_f32_e32 v22, v22, v217
	v_mul_f32_e32 v23, v23, v217
	v_mul_f32_e32 v24, v24, v217
	v_mul_f32_e32 v25, v25, v217
	v_mul_f32_e32 v26, v26, v217
	v_mul_f32_e32 v27, v27, v217
	v_mul_f32_e32 v28, v28, v217
	v_mul_f32_e32 v29, v29, v217
	v_mul_f32_e32 v30, v30, v217
	v_mul_f32_e32 v31, v31, v217
	v_mul_f32_e32 v32, v32, v217
	v_mul_f32_e32 v33, v33, v217
	v_cndmask_b32_e32 v220, v220, v228, vcc
	v_cndmask_b32_e64 v221, v221, -1, vcc
	s_andn2_b64 s[26:27], s[26:27], vcc

.Lna_slow_w0:
	s_cmp_eq_u64 s[40:41], 0
	s_cbranch_scc1 .Lna_sl_a_w0s
	ds_read_b64 v[162:163], v201 offset:0
	ds_read_b64 v[164:165], v201 offset:16
	ds_read_b64 v[166:167], v201 offset:4352
	ds_read_b64 v[168:169], v201 offset:4368
	ds_read_b64 v[170:171], v201 offset:32
	ds_read_b64 v[172:173], v201 offset:48
	ds_read_b64 v[174:175], v201 offset:4384
	ds_read_b64 v[176:177], v201 offset:4400
	v_exp_f32_e32 v34, v34
	v_exp_f32_e32 v35, v35
	v_exp_f32_e32 v36, v36
	v_exp_f32_e32 v37, v37
	v_add_f32_e32 v213, v213, v34
	v_add_f32_e32 v214, v214, v35
	v_add_f32_e32 v213, v213, v36
	v_add_f32_e32 v214, v214, v37
	v_exp_f32_e32 v38, v38
	v_exp_f32_e32 v39, v39
	v_exp_f32_e32 v40, v40
	v_exp_f32_e32 v41, v41
	v_add_f32_e32 v213, v213, v38
	v_add_f32_e32 v214, v214, v39
	v_add_f32_e32 v213, v213, v40
	v_add_f32_e32 v214, v214, v41
	v_cvt_pk_bf16_f32 v34, v34, v35
	v_cvt_pk_bf16_f32 v35, v36, v37
	v_cvt_pk_bf16_f32 v36, v38, v39
	v_cvt_pk_bf16_f32 v37, v40, v41
	v_exp_f32_e32 v42, v42
	v_exp_f32_e32 v43, v43
	v_exp_f32_e32 v44, v44
	v_exp_f32_e32 v45, v45
	v_add_f32_e32 v213, v213, v42
	v_add_f32_e32 v214, v214, v43
	v_add_f32_e32 v213, v213, v44
	v_add_f32_e32 v214, v214, v45
	v_exp_f32_e32 v46, v46
	v_exp_f32_e32 v47, v47
	v_exp_f32_e32 v48, v48
	v_exp_f32_e32 v49, v49
	v_add_f32_e32 v213, v213, v46
	v_add_f32_e32 v214, v214, v47
	v_add_f32_e32 v213, v213, v48
	v_add_f32_e32 v214, v214, v49
	v_cvt_pk_bf16_f32 v42, v42, v43
	v_cvt_pk_bf16_f32 v43, v44, v45
	v_cvt_pk_bf16_f32 v44, v46, v47
	v_cvt_pk_bf16_f32 v45, v48, v49
	s_nop 1
	s_waitcnt lgkmcnt(6)
	v_mfma_f32_32x32x16_bf16 v[2:17], v[162:165], v[34:37], v[2:17]
	s_waitcnt lgkmcnt(4)
	v_mfma_f32_32x32x16_bf16 v[18:33], v[166:169], v[34:37], v[18:33]
	s_waitcnt lgkmcnt(2)
	v_mfma_f32_32x32x16_bf16 v[2:17], v[170:173], v[42:45], v[2:17]
	s_waitcnt lgkmcnt(0)
	v_mfma_f32_32x32x16_bf16 v[18:33], v[174:177], v[42:45], v[18:33]
.Lna_sl_a_w0s:
	s_waitcnt lgkmcnt(0)
	s_cmp_eq_u64 s[42:43], 0
	s_cbranch_scc1 .Lna_sl_b_w0s
	ds_read_b128 v[146:149], v199 offset:9216
	ds_read_b128 v[150:153], v199 offset:9248
	ds_read_b128 v[154:157], v199 offset:9280
	ds_read_b128 v[158:161], v199 offset:9312
	s_waitcnt lgkmcnt(3)
	v_mfma_f32_32x32x16_bf16 v[66:81], v[146:149], v[98:101], v[114:129]
	s_waitcnt lgkmcnt(2)
	v_mfma_f32_32x32x16_bf16 v[66:81], v[150:153], v[102:105], v[66:81]
	s_waitcnt lgkmcnt(1)
	v_mfma_f32_32x32x16_bf16 v[66:81], v[154:157], v[106:109], v[66:81]
	s_waitcnt lgkmcnt(0)
	v_mfma_f32_32x32x16_bf16 v[66:81], v[158:161], v[110:113], v[66:81]
	v_add_u32_e32 v210, s25, v208
	ds_read_b128 v[146:149], v210 offset:0
	ds_read_b128 v[150:153], v210 offset:32
	ds_read_b128 v[154:157], v210 offset:64
	ds_read_b128 v[158:161], v210 offset:96
	s_waitcnt lgkmcnt(0)
	s_nop 15
	v_add_f32_e32 v66, v66, v146
	v_add_f32_e32 v67, v67, v147
	v_add_f32_e32 v68, v68, v148
	v_add_f32_e32 v69, v69, v149
	v_add_f32_e32 v70, v70, v150
	v_add_f32_e32 v71, v71, v151
	v_add_f32_e32 v72, v72, v152
	v_add_f32_e32 v73, v73, v153
	v_add_f32_e32 v74, v74, v154
	v_add_f32_e32 v75, v75, v155
	v_add_f32_e32 v76, v76, v156
	v_add_f32_e32 v77, v77, v157
	v_add_f32_e32 v78, v78, v158
	v_add_f32_e32 v79, v79, v159
	v_add_f32_e32 v80, v80, v160
	v_add_f32_e32 v81, v81, v161
	v_cndmask_b32_e64 v66, v229, v66, s[48:49]
	v_cndmask_b32_e64 v67, v229, v67, s[48:49]
	v_cndmask_b32_e64 v68, v229, v68, s[48:49]
	v_cndmask_b32_e64 v69, v229, v69, s[48:49]
	v_cndmask_b32_e64 v70, v229, v70, s[48:49]
	v_cndmask_b32_e64 v71, v229, v71, s[48:49]
	v_cndmask_b32_e64 v72, v229, v72, s[48:49]
	v_cndmask_b32_e64 v73, v229, v73, s[48:49]
	v_cndmask_b32_e64 v74, v229, v74, s[48:49]
	v_cndmask_b32_e64 v75, v229, v75, s[48:49]
	v_cndmask_b32_e64 v76, v229, v76, s[48:49]
	v_cndmask_b32_e64 v77, v229, v77, s[48:49]
	v_cndmask_b32_e64 v78, v229, v78, s[48:49]
	v_cndmask_b32_e64 v79, v229, v79, s[48:49]
	v_cndmask_b32_e64 v80, v229, v80, s[48:49]
	v_cndmask_b32_e64 v81, v229, v81, s[48:49]
	v_max3_f32 v216, v66, v67, v68
	v_max3_f32 v217, v74, v75, v76
	v_max3_f32 v216, v216, v69, v70
	v_max3_f32 v217, v217, v77, v78
	v_max3_f32 v216, v216, v71, v72
	v_max3_f32 v217, v217, v79, v80
	v_max_f32_e32 v216, v216, v73
	v_max_f32_e32 v217, v217, v81
	v_max_f32_e32 v216, v216, v217
	v_mov_b32_e32 v217, v216
	s_nop 1
	v_permlane32_swap_b32_e32 v216, v217
	v_max_f32_e32 v215, v216, v217
	v_cmp_lt_f32_e32 vcc, 4.0, v215
	s_or_b64 s[28:29], vcc, s[26:27]
	s_cmp_lg_u64 s[28:29], 0
	s_cbranch_scc0 .Lna_nr_w0s
	s_nop 15
	v_max_f32_e32 v216, v215, v220
	v_cmp_lt_f32_e32 vcc, 0xf0c9f2ca, v215
	s_nop 1
	v_cndmask_b32_e32 v216, 0, v216, vcc
	v_exp_f32_e64 v217, -v216
	v_add_f32_e32 v212, v212, v216
	v_and_b32_e32 v217, v217, v221
	v_sub_f32_e32 v66, v66, v216
	v_sub_f32_e32 v67, v67, v216
	v_sub_f32_e32 v68, v68, v216
	v_sub_f32_e32 v69, v69, v216
	v_sub_f32_e32 v70, v70, v216
	v_sub_f32_e32 v71, v71, v216
	v_sub_f32_e32 v72, v72, v216
	v_sub_f32_e32 v73, v73, v216
	v_sub_f32_e32 v74, v74, v216
	v_sub_f32_e32 v75, v75, v216
	v_sub_f32_e32 v76, v76, v216
	v_sub_f32_e32 v77, v77, v216
	v_sub_f32_e32 v78, v78, v216
	v_sub_f32_e32 v79, v79, v216
	v_sub_f32_e32 v80, v80, v216
	v_sub_f32_e32 v81, v81, v216
	v_sub_f32_e32 v114, v114, v216
	v_sub_f32_e32 v115, v115, v216
	v_sub_f32_e32 v116, v116, v216
	v_sub_f32_e32 v117, v117, v216
	v_sub_f32_e32 v118, v118, v216
	v_sub_f32_e32 v119, v119, v216
	v_sub_f32_e32 v120, v120, v216
	v_sub_f32_e32 v121, v121, v216
	v_sub_f32_e32 v122, v122, v216
	v_sub_f32_e32 v123, v123, v216
	v_sub_f32_e32 v124, v124, v216
	v_sub_f32_e32 v125, v125, v216
	v_sub_f32_e32 v126, v126, v216
	v_sub_f32_e32 v127, v127, v216
	v_sub_f32_e32 v128, v128, v216
	v_sub_f32_e32 v129, v129, v216
	v_mul_f32_e32 v213, v213, v217
	v_mul_f32_e32 v214, v214, v217
	v_mul_f32_e32 v2, v2, v217
	v_mul_f32_e32 v3, v3, v217
	v_mul_f32_e32 v4, v4, v217
	v_mul_f32_e32 v5, v5, v217
	v_mul_f32_e32 v6, v6, v217
	v_mul_f32_e32 v7, v7, v217
	v_mul_f32_e32 v8, v8, v217
	v_mul_f32_e32 v9, v9, v217
	v_mul_f32_e32 v10, v10, v217
	v_mul_f32_e32 v11, v11, v217
	v_mul_f32_e32 v12, v12, v217
	v_mul_f32_e32 v13, v13, v217
	v_mul_f32_e32 v14, v14, v217
	v_mul_f32_e32 v15, v15, v217
	v_mul_f32_e32 v16, v16, v217
	v_mul_f32_e32 v17, v17, v217
	v_mul_f32_e32 v18, v18, v217
	v_mul_f32_e32 v19, v19, v217
	v_mul_f32_e32 v20, v20, v217
	v_mul_f32_e32 v21, v21, v217
	v_mul_f32_e32 v22, v22, v217
	v_mul_f32_e32 v23, v23, v217
	v_mul_f32_e32 v24, v24, v217
	v_mul_f32_e32 v25, v25, v217
	v_mul_f32_e32 v26, v26, v217
	v_mul_f32_e32 v27, v27, v217
	v_mul_f32_e32 v28, v28, v217
	v_mul_f32_e32 v29, v29, v217
	v_mul_f32_e32 v30, v30, v217
	v_mul_f32_e32 v31, v31, v217
	v_mul_f32_e32 v32, v32, v217
	v_mul_f32_e32 v33, v33, v217
	v_cndmask_b32_e32 v220, v220, v228, vcc
	v_cndmask_b32_e64 v221, v221, -1, vcc
	s_andn2_b64 s[26:27], s[26:27], vcc

.Lna_done_w0:
	s_add_i32 s24, s24, 1
	s_add_i32 s25, s25, 0x150
	s_add_i32 s33, s33, -1
	s_cmp_lg_u32 s33, 0
	s_cbranch_scc1 .Lna_wloop
	v_sub_f32_e32 v114, 0, v212
	v_mov_b32_e32 v115, v114
	v_mov_b32_e32 v116, v114
	v_mov_b32_e32 v117, v114
	v_mov_b32_e32 v118, v114
	v_mov_b32_e32 v119, v114
	v_mov_b32_e32 v120, v114
	v_mov_b32_e32 v121, v114
	v_mov_b32_e32 v122, v114
	v_mov_b32_e32 v123, v114
	v_mov_b32_e32 v124, v114
	v_mov_b32_e32 v125, v114
	v_mov_b32_e32 v126, v114
	v_mov_b32_e32 v127, v114
	v_mov_b32_e32 v128, v114
	v_mov_b32_e32 v129, v114
	v_mov_b32_e32 v130, v114
	v_mov_b32_e32 v131, v114
	v_mov_b32_e32 v132, v114
	v_mov_b32_e32 v133, v114
	v_mov_b32_e32 v134, v114
	v_mov_b32_e32 v135, v114
	v_mov_b32_e32 v136, v114
	v_mov_b32_e32 v137, v114
	v_mov_b32_e32 v138, v114
	v_mov_b32_e32 v139, v114
	v_mov_b32_e32 v140, v114
	v_mov_b32_e32 v141, v114
	v_mov_b32_e32 v142, v114
	v_mov_b32_e32 v143, v114
	v_mov_b32_e32 v144, v114
	v_mov_b32_e32 v145, v114
	s_sub_i32 s36, s24, s23
	s_cmp_lt_u32 s36, s63
	s_cselect_b64 s[40:41], -1, 0
	s_mov_b64 s[42:43], -1
	s_cmp_eq_u64 s[40:41], 0
	s_cbranch_scc1 .Lna_slow_wc
	ds_read_b128 v[146:149], v200 offset:0
	ds_read_b128 v[150:153], v200 offset:4608
	ds_read_b128 v[154:157], v200 offset:32
	ds_read_b128 v[158:161], v200 offset:4640
	v_exp_f32_e32 v66, v66
	v_exp_f32_e32 v67, v67
	v_exp_f32_e32 v68, v68
	s_waitcnt lgkmcnt(2)
	v_mfma_f32_32x32x16_bf16 v[34:49], v[146:149], v[98:101], v[114:129]
	ds_read_b128 v[146:149], v200 offset:64
	v_exp_f32_e32 v69, v69
	v_add_f32_e32 v213, v213, v66
	v_add_f32_e32 v214, v214, v67
	v_add_f32_e32 v213, v213, v68
	v_add_f32_e32 v214, v214, v69
	v_mfma_f32_32x32x16_bf16 v[50:65], v[150:153], v[98:101], v[130:145]
	ds_read_b128 v[150:153], v200 offset:4672
	v_exp_f32_e32 v70, v70
	v_exp_f32_e32 v71, v71
	v_exp_f32_e32 v72, v72
	s_waitcnt lgkmcnt(2)
	v_mfma_f32_32x32x16_bf16 v[34:49], v[154:157], v[102:105], v[34:49]
	ds_read_b128 v[154:157], v200 offset:96
	v_exp_f32_e32 v73, v73
	v_add_f32_e32 v213, v213, v70
	v_add_f32_e32 v214, v214, v71
	v_add_f32_e32 v213, v213, v72
	v_add_f32_e32 v214, v214, v73
	v_mfma_f32_32x32x16_bf16 v[50:65], v[158:161], v[102:105], v[50:65]
	ds_read_b128 v[158:161], v200 offset:4704
	v_cvt_pk_bf16_f32 v66, v66, v67
	v_cvt_pk_bf16_f32 v67, v68, v69
	v_cvt_pk_bf16_f32 v68, v70, v71
	v_cvt_pk_bf16_f32 v69, v72, v73
	v_exp_f32_e32 v74, v74
	s_waitcnt lgkmcnt(2)
	v_mfma_f32_32x32x16_bf16 v[34:49], v[146:149], v[106:109], v[34:49]
	ds_read_b64 v[162:163], v201 offset:8704
	ds_read_b64 v[164:165], v201 offset:8720
	v_exp_f32_e32 v75, v75
	v_exp_f32_e32 v76, v76
	v_exp_f32_e32 v77, v77
	v_mfma_f32_32x32x16_bf16 v[50:65], v[150:153], v[106:109], v[50:65]
	ds_read_b64 v[166:167], v201 offset:13056
	ds_read_b64 v[168:169], v201 offset:13072
	v_add_f32_e32 v213, v213, v74
	v_add_f32_e32 v214, v214, v75
	v_add_f32_e32 v213, v213, v76
	v_add_f32_e32 v214, v214, v77
	v_exp_f32_e32 v78, v78
	s_waitcnt lgkmcnt(4)
	v_mfma_f32_32x32x16_bf16 v[34:49], v[154:157], v[110:113], v[34:49]
	ds_read_b64 v[170:171], v201 offset:8736
	ds_read_b64 v[172:173], v201 offset:8752
	v_exp_f32_e32 v79, v79
	v_exp_f32_e32 v80, v80
	v_exp_f32_e32 v81, v81
	v_mfma_f32_32x32x16_bf16 v[50:65], v[158:161], v[110:113], v[50:65]
	ds_read_b64 v[174:175], v201 offset:13088
	ds_read_b64 v[176:177], v201 offset:13104
	v_add_f32_e32 v213, v213, v78
	v_add_f32_e32 v214, v214, v79
	v_add_f32_e32 v213, v213, v80
	v_add_f32_e32 v214, v214, v81
	v_cvt_pk_bf16_f32 v74, v74, v75
	v_cvt_pk_bf16_f32 v75, v76, v77
	s_waitcnt lgkmcnt(6)
	v_mfma_f32_32x32x16_bf16 v[2:17], v[162:165], v[66:69], v[2:17]
	v_cvt_pk_bf16_f32 v76, v78, v79
	v_cvt_pk_bf16_f32 v77, v80, v81
	s_waitcnt lgkmcnt(4)
	v_mfma_f32_32x32x16_bf16 v[18:33], v[166:169], v[66:69], v[18:33]
	v_max3_f32 v216, v34, v35, v36
	v_max3_f32 v217, v50, v51, v52
	v_max3_f32 v216, v216, v37, v38
	v_max3_f32 v217, v217, v53, v54
	v_max3_f32 v216, v216, v39, v40
	v_max3_f32 v217, v217, v55, v56
	v_max3_f32 v216, v216, v41, v42
	v_max3_f32 v217, v217, v57, v58
	v_max3_f32 v216, v216, v43, v44
	v_max3_f32 v217, v217, v59, v60
	s_waitcnt lgkmcnt(2)
	v_mfma_f32_32x32x16_bf16 v[2:17], v[170:173], v[74:77], v[2:17]
	v_max3_f32 v216, v216, v45, v46
	v_max3_f32 v217, v217, v61, v62
	v_max3_f32 v216, v216, v47, v48
	v_max3_f32 v217, v217, v63, v64
	v_max_f32_e32 v216, v216, v49
	v_max_f32_e32 v217, v217, v65
	s_waitcnt lgkmcnt(0)
	v_mfma_f32_32x32x16_bf16 v[18:33], v[174:177], v[74:77], v[18:33]
	s_waitcnt vmcnt(2)
	ds_write_b128 v204, v[230:233] offset:9216
	ds_write_b64 v205, v[234:235] offset:0
	ds_write_b64 v205, v[236:237] offset:8
	global_load_dwordx4 v[230:233], v206, s[12:13]
	s_add_u32 s12, s12, 0x2000
	s_addc_u32 s13, s13, 0
	global_load_dwordx4 v[234:237], v207, s[14:15]
	s_add_u32 s14, s14, 0x80
	s_addc_u32 s15, s15, 0
	v_max_f32_e32 v216, v216, v217
	v_mov_b32_e32 v217, v216
	s_nop 1
	v_permlane32_swap_b32_e32 v216, v217
	v_max_f32_e32 v215, v216, v217
	v_cmp_lt_f32_e32 vcc, 4.0, v215
	s_cbranch_vccz .Lna_nr_wcf
	s_nop 15
	v_max_f32_e32 v216, v215, v220
	v_exp_f32_e64 v217, -v216
	v_add_f32_e32 v212, v212, v216
	v_and_b32_e32 v217, v217, v221
	v_sub_f32_e32 v34, v34, v216
	v_sub_f32_e32 v35, v35, v216
	v_sub_f32_e32 v36, v36, v216
	v_sub_f32_e32 v37, v37, v216
	v_sub_f32_e32 v38, v38, v216
	v_sub_f32_e32 v39, v39, v216
	v_sub_f32_e32 v40, v40, v216
	v_sub_f32_e32 v41, v41, v216
	v_sub_f32_e32 v42, v42, v216
	v_sub_f32_e32 v43, v43, v216
	v_sub_f32_e32 v44, v44, v216
	v_sub_f32_e32 v45, v45, v216
	v_sub_f32_e32 v46, v46, v216
	v_sub_f32_e32 v47, v47, v216
	v_sub_f32_e32 v48, v48, v216
	v_sub_f32_e32 v49, v49, v216
	v_sub_f32_e32 v50, v50, v216
	v_sub_f32_e32 v51, v51, v216
	v_sub_f32_e32 v52, v52, v216
	v_sub_f32_e32 v53, v53, v216
	v_sub_f32_e32 v54, v54, v216
	v_sub_f32_e32 v55, v55, v216
	v_sub_f32_e32 v56, v56, v216
	v_sub_f32_e32 v57, v57, v216
	v_sub_f32_e32 v58, v58, v216
	v_sub_f32_e32 v59, v59, v216
	v_sub_f32_e32 v60, v60, v216
	v_sub_f32_e32 v61, v61, v216
	v_sub_f32_e32 v62, v62, v216
	v_sub_f32_e32 v63, v63, v216
	v_sub_f32_e32 v64, v64, v216
	v_sub_f32_e32 v65, v65, v216
	v_sub_f32_e32 v114, v114, v216
	v_sub_f32_e32 v115, v115, v216
	v_sub_f32_e32 v116, v116, v216
	v_sub_f32_e32 v117, v117, v216
	v_sub_f32_e32 v118, v118, v216
	v_sub_f32_e32 v119, v119, v216
	v_sub_f32_e32 v120, v120, v216
	v_sub_f32_e32 v121, v121, v216
	v_sub_f32_e32 v122, v122, v216
	v_sub_f32_e32 v123, v123, v216
	v_sub_f32_e32 v124, v124, v216
	v_sub_f32_e32 v125, v125, v216
	v_sub_f32_e32 v126, v126, v216
	v_sub_f32_e32 v127, v127, v216
	v_sub_f32_e32 v128, v128, v216
	v_sub_f32_e32 v129, v129, v216
	v_sub_f32_e32 v130, v130, v216
	v_sub_f32_e32 v131, v131, v216
	v_sub_f32_e32 v132, v132, v216
	v_sub_f32_e32 v133, v133, v216
	v_sub_f32_e32 v134, v134, v216
	v_sub_f32_e32 v135, v135, v216
	v_sub_f32_e32 v136, v136, v216
	v_sub_f32_e32 v137, v137, v216
	v_sub_f32_e32 v138, v138, v216
	v_sub_f32_e32 v139, v139, v216
	v_sub_f32_e32 v140, v140, v216
	v_sub_f32_e32 v141, v141, v216
	v_sub_f32_e32 v142, v142, v216
	v_sub_f32_e32 v143, v143, v216
	v_sub_f32_e32 v144, v144, v216
	v_sub_f32_e32 v145, v145, v216
	v_mul_f32_e32 v213, v213, v217
	v_mul_f32_e32 v214, v214, v217
	v_mul_f32_e32 v2, v2, v217
	v_mul_f32_e32 v3, v3, v217
	v_mul_f32_e32 v4, v4, v217
	v_mul_f32_e32 v5, v5, v217
	v_mul_f32_e32 v6, v6, v217
	v_mul_f32_e32 v7, v7, v217
	v_mul_f32_e32 v8, v8, v217
	v_mul_f32_e32 v9, v9, v217
	v_mul_f32_e32 v10, v10, v217
	v_mul_f32_e32 v11, v11, v217
	v_mul_f32_e32 v12, v12, v217
	v_mul_f32_e32 v13, v13, v217
	v_mul_f32_e32 v14, v14, v217
	v_mul_f32_e32 v15, v15, v217
	v_mul_f32_e32 v16, v16, v217
	v_mul_f32_e32 v17, v17, v217
	v_mul_f32_e32 v18, v18, v217
	v_mul_f32_e32 v19, v19, v217
	v_mul_f32_e32 v20, v20, v217
	v_mul_f32_e32 v21, v21, v217
	v_mul_f32_e32 v22, v22, v217
	v_mul_f32_e32 v23, v23, v217
	v_mul_f32_e32 v24, v24, v217
	v_mul_f32_e32 v25, v25, v217
	v_mul_f32_e32 v26, v26, v217
	v_mul_f32_e32 v27, v27, v217
	v_mul_f32_e32 v28, v28, v217
	v_mul_f32_e32 v29, v29, v217
	v_mul_f32_e32 v30, v30, v217
	v_mul_f32_e32 v31, v31, v217
	v_mul_f32_e32 v32, v32, v217
	v_mul_f32_e32 v33, v33, v217

.Lna_sl_a_wcs:
	s_waitcnt lgkmcnt(0)
	s_cmp_eq_u64 s[42:43], 0
	s_cbranch_scc1 .Lna_sl_b_wcs
	ds_read_b128 v[146:149], v200 offset:0
	ds_read_b128 v[150:153], v200 offset:4608
	ds_read_b128 v[154:157], v200 offset:32
	ds_read_b128 v[158:161], v200 offset:4640
	ds_read_b128 v[162:165], v200 offset:64
	ds_read_b128 v[166:169], v200 offset:4672
	ds_read_b128 v[170:173], v200 offset:96
	ds_read_b128 v[174:177], v200 offset:4704
	s_waitcnt lgkmcnt(7)
	v_mfma_f32_32x32x16_bf16 v[34:49], v[146:149], v[98:101], v[114:129]
	s_waitcnt lgkmcnt(6)
	v_mfma_f32_32x32x16_bf16 v[50:65], v[150:153], v[98:101], v[130:145]
	s_waitcnt lgkmcnt(5)
	v_mfma_f32_32x32x16_bf16 v[34:49], v[154:157], v[102:105], v[34:49]
	s_waitcnt lgkmcnt(4)
	v_mfma_f32_32x32x16_bf16 v[50:65], v[158:161], v[102:105], v[50:65]
	s_waitcnt lgkmcnt(3)
	v_mfma_f32_32x32x16_bf16 v[34:49], v[162:165], v[106:109], v[34:49]
	s_waitcnt lgkmcnt(2)
	v_mfma_f32_32x32x16_bf16 v[50:65], v[166:169], v[106:109], v[50:65]
	s_waitcnt lgkmcnt(1)
	v_mfma_f32_32x32x16_bf16 v[34:49], v[170:173], v[110:113], v[34:49]
	s_waitcnt lgkmcnt(0)
	v_mfma_f32_32x32x16_bf16 v[50:65], v[174:177], v[110:113], v[50:65]
	s_nop 15
	v_max3_f32 v216, v34, v35, v36
	v_max3_f32 v217, v50, v51, v52
	v_max3_f32 v216, v216, v37, v38
	v_max3_f32 v217, v217, v53, v54
	v_max3_f32 v216, v216, v39, v40
	v_max3_f32 v217, v217, v55, v56
	v_max3_f32 v216, v216, v41, v42
	v_max3_f32 v217, v217, v57, v58
	v_max3_f32 v216, v216, v43, v44
	v_max3_f32 v217, v217, v59, v60
	v_max3_f32 v216, v216, v45, v46
	v_max3_f32 v217, v217, v61, v62
	v_max3_f32 v216, v216, v47, v48
	v_max3_f32 v217, v217, v63, v64
	v_max_f32_e32 v216, v216, v49
	v_max_f32_e32 v217, v217, v65
	v_max_f32_e32 v216, v216, v217
	v_mov_b32_e32 v217, v216
	s_nop 1
	v_permlane32_swap_b32_e32 v216, v217
	v_max_f32_e32 v215, v216, v217
	v_cmp_lt_f32_e32 vcc, 4.0, v215
	s_cbranch_vccz .Lna_nr_wcs
	s_nop 15
	v_max_f32_e32 v216, v215, v220
	v_exp_f32_e64 v217, -v216
	v_add_f32_e32 v212, v212, v216
	v_and_b32_e32 v217, v217, v221
	v_sub_f32_e32 v34, v34, v216
	v_sub_f32_e32 v35, v35, v216
	v_sub_f32_e32 v36, v36, v216
	v_sub_f32_e32 v37, v37, v216
	v_sub_f32_e32 v38, v38, v216
	v_sub_f32_e32 v39, v39, v216
	v_sub_f32_e32 v40, v40, v216
	v_sub_f32_e32 v41, v41, v216
	v_sub_f32_e32 v42, v42, v216
	v_sub_f32_e32 v43, v43, v216
	v_sub_f32_e32 v44, v44, v216
	v_sub_f32_e32 v45, v45, v216
	v_sub_f32_e32 v46, v46, v216
	v_sub_f32_e32 v47, v47, v216
	v_sub_f32_e32 v48, v48, v216
	v_sub_f32_e32 v49, v49, v216
	v_sub_f32_e32 v50, v50, v216
	v_sub_f32_e32 v51, v51, v216
	v_sub_f32_e32 v52, v52, v216
	v_sub_f32_e32 v53, v53, v216
	v_sub_f32_e32 v54, v54, v216
	v_sub_f32_e32 v55, v55, v216
	v_sub_f32_e32 v56, v56, v216
	v_sub_f32_e32 v57, v57, v216
	v_sub_f32_e32 v58, v58, v216
	v_sub_f32_e32 v59, v59, v216
	v_sub_f32_e32 v60, v60, v216
	v_sub_f32_e32 v61, v61, v216
	v_sub_f32_e32 v62, v62, v216
	v_sub_f32_e32 v63, v63, v216
	v_sub_f32_e32 v64, v64, v216
	v_sub_f32_e32 v65, v65, v216
	v_sub_f32_e32 v114, v114, v216
	v_sub_f32_e32 v115, v115, v216
	v_sub_f32_e32 v116, v116, v216
	v_sub_f32_e32 v117, v117, v216
	v_sub_f32_e32 v118, v118, v216
	v_sub_f32_e32 v119, v119, v216
	v_sub_f32_e32 v120, v120, v216
	v_sub_f32_e32 v121, v121, v216
	v_sub_f32_e32 v122, v122, v216
	v_sub_f32_e32 v123, v123, v216
	v_sub_f32_e32 v124, v124, v216
	v_sub_f32_e32 v125, v125, v216
	v_sub_f32_e32 v126, v126, v216
	v_sub_f32_e32 v127, v127, v216
	v_sub_f32_e32 v128, v128, v216
	v_sub_f32_e32 v129, v129, v216
	v_sub_f32_e32 v130, v130, v216
	v_sub_f32_e32 v131, v131, v216
	v_sub_f32_e32 v132, v132, v216
	v_sub_f32_e32 v133, v133, v216
	v_sub_f32_e32 v134, v134, v216
	v_sub_f32_e32 v135, v135, v216
	v_sub_f32_e32 v136, v136, v216
	v_sub_f32_e32 v137, v137, v216
	v_sub_f32_e32 v138, v138, v216
	v_sub_f32_e32 v139, v139, v216
	v_sub_f32_e32 v140, v140, v216
	v_sub_f32_e32 v141, v141, v216
	v_sub_f32_e32 v142, v142, v216
	v_sub_f32_e32 v143, v143, v216
	v_sub_f32_e32 v144, v144, v216
	v_sub_f32_e32 v145, v145, v216
	v_mul_f32_e32 v213, v213, v217
	v_mul_f32_e32 v214, v214, v217
	v_mul_f32_e32 v2, v2, v217
	v_mul_f32_e32 v3, v3, v217
	v_mul_f32_e32 v4, v4, v217
	v_mul_f32_e32 v5, v5, v217
	v_mul_f32_e32 v6, v6, v217
	v_mul_f32_e32 v7, v7, v217
	v_mul_f32_e32 v8, v8, v217
	v_mul_f32_e32 v9, v9, v217
	v_mul_f32_e32 v10, v10, v217
	v_mul_f32_e32 v11, v11, v217
	v_mul_f32_e32 v12, v12, v217
	v_mul_f32_e32 v13, v13, v217
	v_mul_f32_e32 v14, v14, v217
	v_mul_f32_e32 v15, v15, v217
	v_mul_f32_e32 v16, v16, v217
	v_mul_f32_e32 v17, v17, v217
	v_mul_f32_e32 v18, v18, v217
	v_mul_f32_e32 v19, v19, v217
	v_mul_f32_e32 v20, v20, v217
	v_mul_f32_e32 v21, v21, v217
	v_mul_f32_e32 v22, v22, v217
	v_mul_f32_e32 v23, v23, v217
	v_mul_f32_e32 v24, v24, v217
	v_mul_f32_e32 v25, v25, v217
	v_mul_f32_e32 v26, v26, v217
	v_mul_f32_e32 v27, v27, v217
	v_mul_f32_e32 v28, v28, v217
	v_mul_f32_e32 v29, v29, v217
	v_mul_f32_e32 v30, v30, v217
	v_mul_f32_e32 v31, v31, v217
	v_mul_f32_e32 v32, v32, v217
	v_mul_f32_e32 v33, v33, v217

.Lna_done_wc:
	ds_read_b128 v[146:149], v200 offset:9216
	ds_read_b128 v[150:153], v200 offset:13824
	ds_read_b128 v[154:157], v200 offset:9248
	ds_read_b128 v[158:161], v200 offset:13856
	v_exp_f32_e32 v34, v34
	v_exp_f32_e32 v35, v35
	v_exp_f32_e32 v36, v36
	v_exp_f32_e32 v37, v37
	s_waitcnt lgkmcnt(2)
	v_mfma_f32_32x32x16_bf16 v[66:81], v[146:149], v[98:101], v[114:129]
	ds_read_b128 v[146:149], v200 offset:9280
	v_add_f32_e32 v213, v213, v34
	v_add_f32_e32 v214, v214, v35
	v_add_f32_e32 v213, v213, v36
	v_add_f32_e32 v214, v214, v37
	v_exp_f32_e32 v38, v38
	v_exp_f32_e32 v39, v39
	v_mfma_f32_32x32x16_bf16 v[82:97], v[150:153], v[98:101], v[130:145]
	ds_read_b128 v[150:153], v200 offset:13888
	v_exp_f32_e32 v40, v40
	v_exp_f32_e32 v41, v41
	v_add_f32_e32 v213, v213, v38
	v_add_f32_e32 v214, v214, v39
	v_add_f32_e32 v213, v213, v40
	v_add_f32_e32 v214, v214, v41
	s_waitcnt lgkmcnt(2)
	v_mfma_f32_32x32x16_bf16 v[66:81], v[154:157], v[102:105], v[66:81]
	ds_read_b128 v[154:157], v200 offset:9312
	v_cvt_pk_bf16_f32 v34, v34, v35
	v_cvt_pk_bf16_f32 v35, v36, v37
	v_cvt_pk_bf16_f32 v36, v38, v39
	v_cvt_pk_bf16_f32 v37, v40, v41
	v_exp_f32_e32 v42, v42
	v_exp_f32_e32 v43, v43
	v_mfma_f32_32x32x16_bf16 v[82:97], v[158:161], v[102:105], v[82:97]
	ds_read_b128 v[158:161], v200 offset:13920
	v_exp_f32_e32 v44, v44
	v_exp_f32_e32 v45, v45
	v_add_f32_e32 v213, v213, v42
	v_add_f32_e32 v214, v214, v43
	v_add_f32_e32 v213, v213, v44
	v_add_f32_e32 v214, v214, v45
	s_waitcnt lgkmcnt(2)
	v_mfma_f32_32x32x16_bf16 v[66:81], v[146:149], v[106:109], v[66:81]
	ds_read_b64 v[162:163], v202 offset:0
	ds_read_b64 v[164:165], v202 offset:16
	v_exp_f32_e32 v46, v46
	v_exp_f32_e32 v47, v47
	v_exp_f32_e32 v48, v48
	v_exp_f32_e32 v49, v49
	v_mfma_f32_32x32x16_bf16 v[82:97], v[150:153], v[106:109], v[82:97]
	ds_read_b64 v[166:167], v202 offset:4352
	ds_read_b64 v[168:169], v202 offset:4368
	v_add_f32_e32 v213, v213, v46
	v_add_f32_e32 v214, v214, v47
	v_add_f32_e32 v213, v213, v48
	v_add_f32_e32 v214, v214, v49
	v_cvt_pk_bf16_f32 v42, v42, v43
	v_cvt_pk_bf16_f32 v43, v44, v45
	v_cvt_pk_bf16_f32 v44, v46, v47
	v_cvt_pk_bf16_f32 v45, v48, v49
	s_waitcnt lgkmcnt(4)
	v_mfma_f32_32x32x16_bf16 v[66:81], v[154:157], v[110:113], v[66:81]
	ds_read_b64 v[170:171], v202 offset:32
	ds_read_b64 v[172:173], v202 offset:48
	v_exp_f32_e32 v50, v50
	v_exp_f32_e32 v51, v51
	v_exp_f32_e32 v52, v52
	v_exp_f32_e32 v53, v53
	v_mfma_f32_32x32x16_bf16 v[82:97], v[158:161], v[110:113], v[82:97]
	ds_read_b64 v[174:175], v202 offset:4384
	ds_read_b64 v[176:177], v202 offset:4400
	v_add_f32_e32 v213, v213, v50
	v_add_f32_e32 v214, v214, v51
	v_add_f32_e32 v213, v213, v52
	v_add_f32_e32 v214, v214, v53
	v_exp_f32_e32 v54, v54
	v_exp_f32_e32 v55, v55
	s_waitcnt lgkmcnt(6)
	v_mfma_f32_32x32x16_bf16 v[2:17], v[162:165], v[34:37], v[2:17]
	ds_read_b64 v[162:163], v202 offset:64
	ds_read_b64 v[164:165], v202 offset:80
	v_exp_f32_e32 v56, v56
	v_exp_f32_e32 v57, v57
	v_add_f32_e32 v213, v213, v54
	v_add_f32_e32 v214, v214, v55
	v_add_f32_e32 v213, v213, v56
	s_waitcnt lgkmcnt(6)
	v_mfma_f32_32x32x16_bf16 v[18:33], v[166:169], v[34:37], v[18:33]
	ds_read_b64 v[166:167], v202 offset:4416
	ds_read_b64 v[168:169], v202 offset:4432
	v_add_f32_e32 v214, v214, v57
	v_cvt_pk_bf16_f32 v50, v50, v51
	v_cvt_pk_bf16_f32 v51, v52, v53
	v_cvt_pk_bf16_f32 v52, v54, v55
	v_cvt_pk_bf16_f32 v53, v56, v57
	v_exp_f32_e32 v58, v58
	v_exp_f32_e32 v59, v59
	s_waitcnt lgkmcnt(6)
	v_mfma_f32_32x32x16_bf16 v[2:17], v[170:173], v[42:45], v[2:17]
	ds_read_b64 v[170:171], v202 offset:96
	ds_read_b64 v[172:173], v202 offset:112
	v_exp_f32_e32 v60, v60
	v_exp_f32_e32 v61, v61
	v_add_f32_e32 v213, v213, v58
	v_add_f32_e32 v214, v214, v59
	v_add_f32_e32 v213, v213, v60
	s_waitcnt lgkmcnt(6)
	v_mfma_f32_32x32x16_bf16 v[18:33], v[174:177], v[42:45], v[18:33]
	ds_read_b64 v[174:175], v202 offset:4448
	ds_read_b64 v[176:177], v202 offset:4464
	s_waitcnt vmcnt(2)
	ds_write_b128 v204, v[188:191] offset:0
	ds_write_b64 v205, v[192:193] offset:8704
	ds_write_b64 v205, v[194:195] offset:8712
	global_load_dwordx4 v[192:195], v207, s[14:15]
	s_add_u32 s14, s14, 0x80
	s_addc_u32 s15, s15, 0
	v_add_f32_e32 v214, v214, v61
	v_exp_f32_e32 v62, v62
	v_exp_f32_e32 v63, v63
	v_exp_f32_e32 v64, v64
	v_exp_f32_e32 v65, v65
	s_waitcnt lgkmcnt(9)
	v_mfma_f32_32x32x16_bf16 v[2:17], v[162:165], v[50:53], v[2:17]
	v_add_f32_e32 v213, v213, v62
	v_add_f32_e32 v214, v214, v63
	v_add_f32_e32 v213, v213, v64
	v_add_f32_e32 v214, v214, v65
	v_cvt_pk_bf16_f32 v58, v58, v59
	v_cvt_pk_bf16_f32 v59, v60, v61
	v_cvt_pk_bf16_f32 v60, v62, v63
	s_waitcnt lgkmcnt(7)
	v_mfma_f32_32x32x16_bf16 v[18:33], v[166:169], v[50:53], v[18:33]
	v_cvt_pk_bf16_f32 v61, v64, v65
	v_max3_f32 v216, v66, v67, v68
	v_max3_f32 v217, v82, v83, v84
	v_max3_f32 v216, v216, v69, v70
	v_max3_f32 v217, v217, v85, v86
	v_max3_f32 v216, v216, v71, v72
	v_max3_f32 v217, v217, v87, v88
	v_max3_f32 v216, v216, v73, v74
	s_waitcnt lgkmcnt(5)
	v_mfma_f32_32x32x16_bf16 v[2:17], v[170:173], v[58:61], v[2:17]
	v_max3_f32 v217, v217, v89, v90
	v_max3_f32 v216, v216, v75, v76
	v_max3_f32 v217, v217, v91, v92
	v_max3_f32 v216, v216, v77, v78
	v_max3_f32 v217, v217, v93, v94
	v_max3_f32 v216, v216, v79, v80
	v_max3_f32 v217, v217, v95, v96
	v_max_f32_e32 v216, v216, v81
	s_waitcnt lgkmcnt(3)
	v_mfma_f32_32x32x16_bf16 v[18:33], v[174:177], v[58:61], v[18:33]
	v_max_f32_e32 v217, v217, v97
	v_max_f32_e32 v216, v216, v217
	v_mov_b32_e32 v217, v216
	s_nop 1
	v_permlane32_swap_b32_e32 v216, v217
	v_max_f32_e32 v215, v216, v217
	v_cmp_lt_f32_e32 vcc, 4.0, v215
	s_cbranch_vccz .Lna_nr_c0
	s_nop 15
	v_max_f32_e32 v216, v215, v220
	v_exp_f32_e64 v217, -v216
	v_add_f32_e32 v212, v212, v216
	v_and_b32_e32 v217, v217, v221
	v_sub_f32_e32 v66, v66, v216
	v_sub_f32_e32 v67, v67, v216
	v_sub_f32_e32 v68, v68, v216
	v_sub_f32_e32 v69, v69, v216
	v_sub_f32_e32 v70, v70, v216
	v_sub_f32_e32 v71, v71, v216
	v_sub_f32_e32 v72, v72, v216
	v_sub_f32_e32 v73, v73, v216
	v_sub_f32_e32 v74, v74, v216
	v_sub_f32_e32 v75, v75, v216
	v_sub_f32_e32 v76, v76, v216
	v_sub_f32_e32 v77, v77, v216
	v_sub_f32_e32 v78, v78, v216
	v_sub_f32_e32 v79, v79, v216
	v_sub_f32_e32 v80, v80, v216
	v_sub_f32_e32 v81, v81, v216
	v_sub_f32_e32 v82, v82, v216
	v_sub_f32_e32 v83, v83, v216
	v_sub_f32_e32 v84, v84, v216
	v_sub_f32_e32 v85, v85, v216
	v_sub_f32_e32 v86, v86, v216
	v_sub_f32_e32 v87, v87, v216
	v_sub_f32_e32 v88, v88, v216
	v_sub_f32_e32 v89, v89, v216
	v_sub_f32_e32 v90, v90, v216
	v_sub_f32_e32 v91, v91, v216
	v_sub_f32_e32 v92, v92, v216
	v_sub_f32_e32 v93, v93, v216
	v_sub_f32_e32 v94, v94, v216
	v_sub_f32_e32 v95, v95, v216
	v_sub_f32_e32 v96, v96, v216
	v_sub_f32_e32 v97, v97, v216
	v_sub_f32_e32 v114, v114, v216
	v_sub_f32_e32 v115, v115, v216
	v_sub_f32_e32 v116, v116, v216
	v_sub_f32_e32 v117, v117, v216
	v_sub_f32_e32 v118, v118, v216
	v_sub_f32_e32 v119, v119, v216
	v_sub_f32_e32 v120, v120, v216
	v_sub_f32_e32 v121, v121, v216
	v_sub_f32_e32 v122, v122, v216
	v_sub_f32_e32 v123, v123, v216
	v_sub_f32_e32 v124, v124, v216
	v_sub_f32_e32 v125, v125, v216
	v_sub_f32_e32 v126, v126, v216
	v_sub_f32_e32 v127, v127, v216
	v_sub_f32_e32 v128, v128, v216
	v_sub_f32_e32 v129, v129, v216
	v_sub_f32_e32 v130, v130, v216
	v_sub_f32_e32 v131, v131, v216
	v_sub_f32_e32 v132, v132, v216
	v_sub_f32_e32 v133, v133, v216
	v_sub_f32_e32 v134, v134, v216
	v_sub_f32_e32 v135, v135, v216
	v_sub_f32_e32 v136, v136, v216
	v_sub_f32_e32 v137, v137, v216
	v_sub_f32_e32 v138, v138, v216
	v_sub_f32_e32 v139, v139, v216
	v_sub_f32_e32 v140, v140, v216
	v_sub_f32_e32 v141, v141, v216
	v_sub_f32_e32 v142, v142, v216
	v_sub_f32_e32 v143, v143, v216
	v_sub_f32_e32 v144, v144, v216
	v_sub_f32_e32 v145, v145, v216
	v_mul_f32_e32 v213, v213, v217
	v_mul_f32_e32 v214, v214, v217
	v_mul_f32_e32 v2, v2, v217
	v_mul_f32_e32 v3, v3, v217
	v_mul_f32_e32 v4, v4, v217
	v_mul_f32_e32 v5, v5, v217
	v_mul_f32_e32 v6, v6, v217
	v_mul_f32_e32 v7, v7, v217
	v_mul_f32_e32 v8, v8, v217
	v_mul_f32_e32 v9, v9, v217
	v_mul_f32_e32 v10, v10, v217
	v_mul_f32_e32 v11, v11, v217
	v_mul_f32_e32 v12, v12, v217
	v_mul_f32_e32 v13, v13, v217
	v_mul_f32_e32 v14, v14, v217
	v_mul_f32_e32 v15, v15, v217
	v_mul_f32_e32 v16, v16, v217
	v_mul_f32_e32 v17, v17, v217
	v_mul_f32_e32 v18, v18, v217
	v_mul_f32_e32 v19, v19, v217
	v_mul_f32_e32 v20, v20, v217
	v_mul_f32_e32 v21, v21, v217
	v_mul_f32_e32 v22, v22, v217
	v_mul_f32_e32 v23, v23, v217
	v_mul_f32_e32 v24, v24, v217
	v_mul_f32_e32 v25, v25, v217
	v_mul_f32_e32 v26, v26, v217
	v_mul_f32_e32 v27, v27, v217
	v_mul_f32_e32 v28, v28, v217
	v_mul_f32_e32 v29, v29, v217
	v_mul_f32_e32 v30, v30, v217
	v_mul_f32_e32 v31, v31, v217
	v_mul_f32_e32 v32, v32, v217
	v_mul_f32_e32 v33, v33, v217
.Lna_nr_c0:
	s_waitcnt lgkmcnt(0)
	s_barrier
	ds_read_b128 v[146:149], v200 offset:0
	ds_read_b128 v[150:153], v200 offset:4608
	ds_read_b128 v[154:157], v200 offset:32
	ds_read_b128 v[158:161], v200 offset:4640
	v_exp_f32_e32 v66, v66
	v_exp_f32_e32 v67, v67
	v_exp_f32_e32 v68, v68
	v_exp_f32_e32 v69, v69
	s_waitcnt lgkmcnt(2)
	v_mfma_f32_32x32x16_bf16 v[34:49], v[146:149], v[98:101], v[114:129]
	ds_read_b128 v[146:149], v200 offset:64
	v_add_f32_e32 v213, v213, v66
	v_add_f32_e32 v214, v214, v67
	v_add_f32_e32 v213, v213, v68
	v_add_f32_e32 v214, v214, v69
	v_exp_f32_e32 v70, v70
	v_exp_f32_e32 v71, v71
	v_mfma_f32_32x32x16_bf16 v[50:65], v[150:153], v[98:101], v[130:145]
	ds_read_b128 v[150:153], v200 offset:4672
	v_exp_f32_e32 v72, v72
	v_exp_f32_e32 v73, v73
	v_add_f32_e32 v213, v213, v70
	v_add_f32_e32 v214, v214, v71
	v_add_f32_e32 v213, v213, v72
	v_add_f32_e32 v214, v214, v73
	s_waitcnt lgkmcnt(2)
	v_mfma_f32_32x32x16_bf16 v[34:49], v[154:157], v[102:105], v[34:49]
	ds_read_b128 v[154:157], v200 offset:96
	v_cvt_pk_bf16_f32 v66, v66, v67
	v_cvt_pk_bf16_f32 v67, v68, v69
	v_cvt_pk_bf16_f32 v68, v70, v71
	v_cvt_pk_bf16_f32 v69, v72, v73
	v_exp_f32_e32 v74, v74
	v_exp_f32_e32 v75, v75
	v_mfma_f32_32x32x16_bf16 v[50:65], v[158:161], v[102:105], v[50:65]
	ds_read_b128 v[158:161], v200 offset:4704
	v_exp_f32_e32 v76, v76
	v_exp_f32_e32 v77, v77
	v_add_f32_e32 v213, v213, v74
	v_add_f32_e32 v214, v214, v75
	v_add_f32_e32 v213, v213, v76
	v_add_f32_e32 v214, v214, v77
	s_waitcnt lgkmcnt(2)
	v_mfma_f32_32x32x16_bf16 v[34:49], v[146:149], v[106:109], v[34:49]
	ds_read_b64 v[162:163], v202 offset:8704
	ds_read_b64 v[164:165], v202 offset:8720
	v_exp_f32_e32 v78, v78
	v_exp_f32_e32 v79, v79
	v_exp_f32_e32 v80, v80
	v_exp_f32_e32 v81, v81
	v_mfma_f32_32x32x16_bf16 v[50:65], v[150:153], v[106:109], v[50:65]
	ds_read_b64 v[166:167], v202 offset:13056
	ds_read_b64 v[168:169], v202 offset:13072
	v_add_f32_e32 v213, v213, v78
	v_add_f32_e32 v214, v214, v79
	v_add_f32_e32 v213, v213, v80
	v_add_f32_e32 v214, v214, v81
	v_cvt_pk_bf16_f32 v74, v74, v75
	v_cvt_pk_bf16_f32 v75, v76, v77
	v_cvt_pk_bf16_f32 v76, v78, v79
	v_cvt_pk_bf16_f32 v77, v80, v81
	s_waitcnt lgkmcnt(4)
	v_mfma_f32_32x32x16_bf16 v[34:49], v[154:157], v[110:113], v[34:49]
	ds_read_b64 v[170:171], v202 offset:8736
	ds_read_b64 v[172:173], v202 offset:8752
	v_exp_f32_e32 v82, v82
	v_exp_f32_e32 v83, v83
	v_exp_f32_e32 v84, v84
	v_exp_f32_e32 v85, v85
	v_mfma_f32_32x32x16_bf16 v[50:65], v[158:161], v[110:113], v[50:65]
	ds_read_b64 v[174:175], v202 offset:13088
	ds_read_b64 v[176:177], v202 offset:13104
	v_add_f32_e32 v213, v213, v82
	v_add_f32_e32 v214, v214, v83
	v_add_f32_e32 v213, v213, v84
	v_add_f32_e32 v214, v214, v85
	v_exp_f32_e32 v86, v86
	v_exp_f32_e32 v87, v87
	s_waitcnt lgkmcnt(6)
	v_mfma_f32_32x32x16_bf16 v[2:17], v[162:165], v[66:69], v[2:17]
	ds_read_b64 v[162:163], v202 offset:8768
	ds_read_b64 v[164:165], v202 offset:8784
	v_exp_f32_e32 v88, v88
	v_exp_f32_e32 v89, v89
	v_add_f32_e32 v213, v213, v86
	v_add_f32_e32 v214, v214, v87
	v_add_f32_e32 v213, v213, v88
	s_waitcnt lgkmcnt(6)
	v_mfma_f32_32x32x16_bf16 v[18:33], v[166:169], v[66:69], v[18:33]
	ds_read_b64 v[166:167], v202 offset:13120
	ds_read_b64 v[168:169], v202 offset:13136
	v_add_f32_e32 v214, v214, v89
	v_cvt_pk_bf16_f32 v82, v82, v83
	v_cvt_pk_bf16_f32 v83, v84, v85
	v_cvt_pk_bf16_f32 v84, v86, v87
	v_cvt_pk_bf16_f32 v85, v88, v89
	v_exp_f32_e32 v90, v90
	v_exp_f32_e32 v91, v91
	s_waitcnt lgkmcnt(6)
	v_mfma_f32_32x32x16_bf16 v[2:17], v[170:173], v[74:77], v[2:17]
	ds_read_b64 v[170:171], v202 offset:8800
	ds_read_b64 v[172:173], v202 offset:8816
	v_exp_f32_e32 v92, v92
	v_exp_f32_e32 v93, v93
	v_add_f32_e32 v213, v213, v90
	v_add_f32_e32 v214, v214, v91
	v_add_f32_e32 v213, v213, v92
	s_waitcnt lgkmcnt(6)
	v_mfma_f32_32x32x16_bf16 v[18:33], v[174:177], v[74:77], v[18:33]
	ds_read_b64 v[174:175], v202 offset:13152
	ds_read_b64 v[176:177], v202 offset:13168
	s_waitcnt vmcnt(1)
	ds_write_b128 v204, v[230:233] offset:9216
	ds_write_b64 v205, v[234:235] offset:0
	ds_write_b64 v205, v[236:237] offset:8
	v_add_f32_e32 v214, v214, v93
	v_exp_f32_e32 v94, v94
	v_exp_f32_e32 v95, v95
	v_exp_f32_e32 v96, v96
	v_exp_f32_e32 v97, v97
	s_waitcnt lgkmcnt(9)
	v_mfma_f32_32x32x16_bf16 v[2:17], v[162:165], v[82:85], v[2:17]
	v_add_f32_e32 v213, v213, v94
	v_add_f32_e32 v214, v214, v95
	v_add_f32_e32 v213, v213, v96
	v_add_f32_e32 v214, v214, v97
	v_cvt_pk_bf16_f32 v90, v90, v91
	v_cvt_pk_bf16_f32 v91, v92, v93
	v_cvt_pk_bf16_f32 v92, v94, v95
	s_waitcnt lgkmcnt(7)
	v_mfma_f32_32x32x16_bf16 v[18:33], v[166:169], v[82:85], v[18:33]
	v_cvt_pk_bf16_f32 v93, v96, v97
	v_max3_f32 v216, v34, v35, v36
	v_max3_f32 v217, v50, v51, v52
	v_max3_f32 v216, v216, v37, v38
	v_max3_f32 v217, v217, v53, v54
	v_max3_f32 v216, v216, v39, v40
	v_max3_f32 v217, v217, v55, v56
	v_max3_f32 v216, v216, v41, v42
	s_waitcnt lgkmcnt(5)
	v_mfma_f32_32x32x16_bf16 v[2:17], v[170:173], v[90:93], v[2:17]
	v_max3_f32 v217, v217, v57, v58
	v_max3_f32 v216, v216, v43, v44
	v_max3_f32 v217, v217, v59, v60
	v_max3_f32 v216, v216, v45, v46
	v_max3_f32 v217, v217, v61, v62
	v_max3_f32 v216, v216, v47, v48
	v_max3_f32 v217, v217, v63, v64
	v_max_f32_e32 v216, v216, v49
	s_waitcnt lgkmcnt(3)
	v_mfma_f32_32x32x16_bf16 v[18:33], v[174:177], v[90:93], v[18:33]
	v_max_f32_e32 v217, v217, v65
	v_max_f32_e32 v216, v216, v217
	v_mov_b32_e32 v217, v216
	s_nop 1
	v_permlane32_swap_b32_e32 v216, v217
	v_max_f32_e32 v215, v216, v217
	v_cmp_lt_f32_e32 vcc, 4.0, v215
	s_cbranch_vccz .Lna_nr_c1
	s_nop 15
	v_max_f32_e32 v216, v215, v220
	v_exp_f32_e64 v217, -v216
	v_add_f32_e32 v212, v212, v216
	v_and_b32_e32 v217, v217, v221
	v_sub_f32_e32 v34, v34, v216
	v_sub_f32_e32 v35, v35, v216
	v_sub_f32_e32 v36, v36, v216
	v_sub_f32_e32 v37, v37, v216
	v_sub_f32_e32 v38, v38, v216
	v_sub_f32_e32 v39, v39, v216
	v_sub_f32_e32 v40, v40, v216
	v_sub_f32_e32 v41, v41, v216
	v_sub_f32_e32 v42, v42, v216
	v_sub_f32_e32 v43, v43, v216
	v_sub_f32_e32 v44, v44, v216
	v_sub_f32_e32 v45, v45, v216
	v_sub_f32_e32 v46, v46, v216
	v_sub_f32_e32 v47, v47, v216
	v_sub_f32_e32 v48, v48, v216
	v_sub_f32_e32 v49, v49, v216
	v_sub_f32_e32 v50, v50, v216
	v_sub_f32_e32 v51, v51, v216
	v_sub_f32_e32 v52, v52, v216
	v_sub_f32_e32 v53, v53, v216
	v_sub_f32_e32 v54, v54, v216
	v_sub_f32_e32 v55, v55, v216
	v_sub_f32_e32 v56, v56, v216
	v_sub_f32_e32 v57, v57, v216
	v_sub_f32_e32 v58, v58, v216
	v_sub_f32_e32 v59, v59, v216
	v_sub_f32_e32 v60, v60, v216
	v_sub_f32_e32 v61, v61, v216
	v_sub_f32_e32 v62, v62, v216
	v_sub_f32_e32 v63, v63, v216
	v_sub_f32_e32 v64, v64, v216
	v_sub_f32_e32 v65, v65, v216
	v_sub_f32_e32 v114, v114, v216
	v_sub_f32_e32 v115, v115, v216
	v_sub_f32_e32 v116, v116, v216
	v_sub_f32_e32 v117, v117, v216
	v_sub_f32_e32 v118, v118, v216
	v_sub_f32_e32 v119, v119, v216
	v_sub_f32_e32 v120, v120, v216
	v_sub_f32_e32 v121, v121, v216
	v_sub_f32_e32 v122, v122, v216
	v_sub_f32_e32 v123, v123, v216
	v_sub_f32_e32 v124, v124, v216
	v_sub_f32_e32 v125, v125, v216
	v_sub_f32_e32 v126, v126, v216
	v_sub_f32_e32 v127, v127, v216
	v_sub_f32_e32 v128, v128, v216
	v_sub_f32_e32 v129, v129, v216
	v_sub_f32_e32 v130, v130, v216
	v_sub_f32_e32 v131, v131, v216
	v_sub_f32_e32 v132, v132, v216
	v_sub_f32_e32 v133, v133, v216
	v_sub_f32_e32 v134, v134, v216
	v_sub_f32_e32 v135, v135, v216
	v_sub_f32_e32 v136, v136, v216
	v_sub_f32_e32 v137, v137, v216
	v_sub_f32_e32 v138, v138, v216
	v_sub_f32_e32 v139, v139, v216
	v_sub_f32_e32 v140, v140, v216
	v_sub_f32_e32 v141, v141, v216
	v_sub_f32_e32 v142, v142, v216
	v_sub_f32_e32 v143, v143, v216
	v_sub_f32_e32 v144, v144, v216
	v_sub_f32_e32 v145, v145, v216
	v_mul_f32_e32 v213, v213, v217
	v_mul_f32_e32 v214, v214, v217
	v_mul_f32_e32 v2, v2, v217
	v_mul_f32_e32 v3, v3, v217
	v_mul_f32_e32 v4, v4, v217
	v_mul_f32_e32 v5, v5, v217
	v_mul_f32_e32 v6, v6, v217
	v_mul_f32_e32 v7, v7, v217
	v_mul_f32_e32 v8, v8, v217
	v_mul_f32_e32 v9, v9, v217
	v_mul_f32_e32 v10, v10, v217
	v_mul_f32_e32 v11, v11, v217
	v_mul_f32_e32 v12, v12, v217
	v_mul_f32_e32 v13, v13, v217
	v_mul_f32_e32 v14, v14, v217
	v_mul_f32_e32 v15, v15, v217
	v_mul_f32_e32 v16, v16, v217
	v_mul_f32_e32 v17, v17, v217
	v_mul_f32_e32 v18, v18, v217
	v_mul_f32_e32 v19, v19, v217
	v_mul_f32_e32 v20, v20, v217
	v_mul_f32_e32 v21, v21, v217
	v_mul_f32_e32 v22, v22, v217
	v_mul_f32_e32 v23, v23, v217
	v_mul_f32_e32 v24, v24, v217
	v_mul_f32_e32 v25, v25, v217
	v_mul_f32_e32 v26, v26, v217
	v_mul_f32_e32 v27, v27, v217
	v_mul_f32_e32 v28, v28, v217
	v_mul_f32_e32 v29, v29, v217
	v_mul_f32_e32 v30, v30, v217
	v_mul_f32_e32 v31, v31, v217
	v_mul_f32_e32 v32, v32, v217
	v_mul_f32_e32 v33, v33, v217
.Lna_nr_c1:
	s_waitcnt lgkmcnt(0)
	s_barrier
	ds_read_b128 v[146:149], v200 offset:9216
	ds_read_b128 v[150:153], v200 offset:13824
	ds_read_b128 v[154:157], v200 offset:9248
	ds_read_b128 v[158:161], v200 offset:13856
	v_exp_f32_e32 v34, v34
	v_exp_f32_e32 v35, v35
	v_exp_f32_e32 v36, v36
	v_exp_f32_e32 v37, v37
	s_waitcnt lgkmcnt(2)
	v_mfma_f32_32x32x16_bf16 v[66:81], v[146:149], v[98:101], v[114:129]
	ds_read_b128 v[146:149], v200 offset:9280
	v_add_f32_e32 v213, v213, v34
	v_add_f32_e32 v214, v214, v35
	v_add_f32_e32 v213, v213, v36
	v_add_f32_e32 v214, v214, v37
	v_exp_f32_e32 v38, v38
	v_exp_f32_e32 v39, v39
	v_mfma_f32_32x32x16_bf16 v[82:97], v[150:153], v[98:101], v[130:145]
	ds_read_b128 v[150:153], v200 offset:13888
	v_exp_f32_e32 v40, v40
	v_exp_f32_e32 v41, v41
	v_add_f32_e32 v213, v213, v38
	v_add_f32_e32 v214, v214, v39
	v_add_f32_e32 v213, v213, v40
	v_add_f32_e32 v214, v214, v41
	s_waitcnt lgkmcnt(2)
	v_mfma_f32_32x32x16_bf16 v[66:81], v[154:157], v[102:105], v[66:81]
	ds_read_b128 v[154:157], v200 offset:9312
	v_cvt_pk_bf16_f32 v34, v34, v35
	v_cvt_pk_bf16_f32 v35, v36, v37
	v_cvt_pk_bf16_f32 v36, v38, v39
	v_cvt_pk_bf16_f32 v37, v40, v41
	v_exp_f32_e32 v42, v42
	v_exp_f32_e32 v43, v43
	v_mfma_f32_32x32x16_bf16 v[82:97], v[158:161], v[102:105], v[82:97]
	ds_read_b128 v[158:161], v200 offset:13920
	v_exp_f32_e32 v44, v44
	v_exp_f32_e32 v45, v45
	v_add_f32_e32 v213, v213, v42
	v_add_f32_e32 v214, v214, v43
	v_add_f32_e32 v213, v213, v44
	v_add_f32_e32 v214, v214, v45
	s_waitcnt lgkmcnt(2)
	v_mfma_f32_32x32x16_bf16 v[66:81], v[146:149], v[106:109], v[66:81]
	ds_read_b64 v[162:163], v202 offset:0
	ds_read_b64 v[164:165], v202 offset:16
	v_exp_f32_e32 v46, v46
	v_exp_f32_e32 v47, v47
	v_exp_f32_e32 v48, v48
	v_exp_f32_e32 v49, v49
	v_mfma_f32_32x32x16_bf16 v[82:97], v[150:153], v[106:109], v[82:97]
	ds_read_b64 v[166:167], v202 offset:4352
	ds_read_b64 v[168:169], v202 offset:4368
	v_add_f32_e32 v213, v213, v46
	v_add_f32_e32 v214, v214, v47
	v_add_f32_e32 v213, v213, v48
	v_add_f32_e32 v214, v214, v49
	v_cvt_pk_bf16_f32 v42, v42, v43
	v_cvt_pk_bf16_f32 v43, v44, v45
	v_cvt_pk_bf16_f32 v44, v46, v47
	v_cvt_pk_bf16_f32 v45, v48, v49
	s_waitcnt lgkmcnt(4)
	v_mfma_f32_32x32x16_bf16 v[66:81], v[154:157], v[110:113], v[66:81]
	ds_read_b64 v[170:171], v202 offset:32
	ds_read_b64 v[172:173], v202 offset:48
	v_exp_f32_e32 v50, v50
	v_exp_f32_e32 v51, v51
	v_exp_f32_e32 v52, v52
	v_exp_f32_e32 v53, v53
	v_mfma_f32_32x32x16_bf16 v[82:97], v[158:161], v[110:113], v[82:97]
	ds_read_b64 v[174:175], v202 offset:4384
	ds_read_b64 v[176:177], v202 offset:4400
	v_add_f32_e32 v213, v213, v50
	v_add_f32_e32 v214, v214, v51
	v_add_f32_e32 v213, v213, v52
	v_add_f32_e32 v214, v214, v53
	v_exp_f32_e32 v54, v54
	v_exp_f32_e32 v55, v55
	s_waitcnt lgkmcnt(6)
	v_mfma_f32_32x32x16_bf16 v[2:17], v[162:165], v[34:37], v[2:17]
	ds_read_b64 v[162:163], v202 offset:64
	ds_read_b64 v[164:165], v202 offset:80
	v_exp_f32_e32 v56, v56
	v_exp_f32_e32 v57, v57
	v_add_f32_e32 v213, v213, v54
	v_add_f32_e32 v214, v214, v55
	v_add_f32_e32 v213, v213, v56
	s_waitcnt lgkmcnt(6)
	v_mfma_f32_32x32x16_bf16 v[18:33], v[166:169], v[34:37], v[18:33]
	ds_read_b64 v[166:167], v202 offset:4416
	ds_read_b64 v[168:169], v202 offset:4432
	v_add_f32_e32 v214, v214, v57
	v_cvt_pk_bf16_f32 v50, v50, v51
	v_cvt_pk_bf16_f32 v51, v52, v53
	v_cvt_pk_bf16_f32 v52, v54, v55
	v_cvt_pk_bf16_f32 v53, v56, v57
	v_exp_f32_e32 v58, v58
	v_exp_f32_e32 v59, v59
	s_waitcnt lgkmcnt(6)
	v_mfma_f32_32x32x16_bf16 v[2:17], v[170:173], v[42:45], v[2:17]
	ds_read_b64 v[170:171], v202 offset:96
	ds_read_b64 v[172:173], v202 offset:112
	v_exp_f32_e32 v60, v60
	v_exp_f32_e32 v61, v61
	v_add_f32_e32 v213, v213, v58
	v_add_f32_e32 v214, v214, v59
	v_add_f32_e32 v213, v213, v60
	s_waitcnt lgkmcnt(6)
	v_mfma_f32_32x32x16_bf16 v[18:33], v[174:177], v[42:45], v[18:33]
	ds_read_b64 v[174:175], v202 offset:4448
	ds_read_b64 v[176:177], v202 offset:4464
	s_waitcnt vmcnt(0)
	ds_write_b64 v205, v[192:193] offset:8704
	ds_write_b64 v205, v[194:195] offset:8712
	v_add_f32_e32 v214, v214, v61
	v_exp_f32_e32 v62, v62
	v_exp_f32_e32 v63, v63
	v_exp_f32_e32 v64, v64
	v_exp_f32_e32 v65, v65
	s_waitcnt lgkmcnt(8)
	v_mfma_f32_32x32x16_bf16 v[2:17], v[162:165], v[50:53], v[2:17]
	v_add_f32_e32 v213, v213, v62
	v_add_f32_e32 v214, v214, v63
	v_add_f32_e32 v213, v213, v64
	v_add_f32_e32 v214, v214, v65
	v_cvt_pk_bf16_f32 v58, v58, v59
	v_cvt_pk_bf16_f32 v59, v60, v61
	v_cvt_pk_bf16_f32 v60, v62, v63
	s_waitcnt lgkmcnt(6)
	v_mfma_f32_32x32x16_bf16 v[18:33], v[166:169], v[50:53], v[18:33]
	v_cvt_pk_bf16_f32 v61, v64, v65
	v_max3_f32 v216, v66, v67, v68
	v_max3_f32 v217, v82, v83, v84
	v_max3_f32 v216, v216, v69, v70
	v_max3_f32 v217, v217, v85, v86
	v_max3_f32 v216, v216, v71, v72
	v_max3_f32 v217, v217, v87, v88
	v_max3_f32 v216, v216, v73, v74
	s_waitcnt lgkmcnt(4)
	v_mfma_f32_32x32x16_bf16 v[2:17], v[170:173], v[58:61], v[2:17]
	v_max3_f32 v217, v217, v89, v90
	v_max3_f32 v216, v216, v75, v76
	v_max3_f32 v217, v217, v91, v92
	v_max3_f32 v216, v216, v77, v78
	v_max3_f32 v217, v217, v93, v94
	v_max3_f32 v216, v216, v79, v80
	v_max3_f32 v217, v217, v95, v96
	v_max_f32_e32 v216, v216, v81
	s_waitcnt lgkmcnt(2)
	v_mfma_f32_32x32x16_bf16 v[18:33], v[174:177], v[58:61], v[18:33]
	v_max_f32_e32 v217, v217, v97
	v_max_f32_e32 v216, v216, v217
	v_mov_b32_e32 v217, v216
	s_nop 1
	v_permlane32_swap_b32_e32 v216, v217
	v_max_f32_e32 v215, v216, v217
	v_cmp_lt_f32_e32 vcc, 4.0, v215
	s_cbranch_vccz .Lna_nr_c2
	s_nop 15
	v_max_f32_e32 v216, v215, v220
	v_exp_f32_e64 v217, -v216
	v_add_f32_e32 v212, v212, v216
	v_and_b32_e32 v217, v217, v221
	v_sub_f32_e32 v66, v66, v216
	v_sub_f32_e32 v67, v67, v216
	v_sub_f32_e32 v68, v68, v216
	v_sub_f32_e32 v69, v69, v216
	v_sub_f32_e32 v70, v70, v216
	v_sub_f32_e32 v71, v71, v216
	v_sub_f32_e32 v72, v72, v216
	v_sub_f32_e32 v73, v73, v216
	v_sub_f32_e32 v74, v74, v216
	v_sub_f32_e32 v75, v75, v216
	v_sub_f32_e32 v76, v76, v216
	v_sub_f32_e32 v77, v77, v216
	v_sub_f32_e32 v78, v78, v216
	v_sub_f32_e32 v79, v79, v216
	v_sub_f32_e32 v80, v80, v216
	v_sub_f32_e32 v81, v81, v216
	v_sub_f32_e32 v82, v82, v216
	v_sub_f32_e32 v83, v83, v216
	v_sub_f32_e32 v84, v84, v216
	v_sub_f32_e32 v85, v85, v216
	v_sub_f32_e32 v86, v86, v216
	v_sub_f32_e32 v87, v87, v216
	v_sub_f32_e32 v88, v88, v216
	v_sub_f32_e32 v89, v89, v216
	v_sub_f32_e32 v90, v90, v216
	v_sub_f32_e32 v91, v91, v216
	v_sub_f32_e32 v92, v92, v216
	v_sub_f32_e32 v93, v93, v216
	v_sub_f32_e32 v94, v94, v216
	v_sub_f32_e32 v95, v95, v216
	v_sub_f32_e32 v96, v96, v216
	v_sub_f32_e32 v97, v97, v216
	v_sub_f32_e32 v114, v114, v216
	v_sub_f32_e32 v115, v115, v216
	v_sub_f32_e32 v116, v116, v216
	v_sub_f32_e32 v117, v117, v216
	v_sub_f32_e32 v118, v118, v216
	v_sub_f32_e32 v119, v119, v216
	v_sub_f32_e32 v120, v120, v216
	v_sub_f32_e32 v121, v121, v216
	v_sub_f32_e32 v122, v122, v216
	v_sub_f32_e32 v123, v123, v216
	v_sub_f32_e32 v124, v124, v216
	v_sub_f32_e32 v125, v125, v216
	v_sub_f32_e32 v126, v126, v216
	v_sub_f32_e32 v127, v127, v216
	v_sub_f32_e32 v128, v128, v216
	v_sub_f32_e32 v129, v129, v216
	v_sub_f32_e32 v130, v130, v216
	v_sub_f32_e32 v131, v131, v216
	v_sub_f32_e32 v132, v132, v216
	v_sub_f32_e32 v133, v133, v216
	v_sub_f32_e32 v134, v134, v216
	v_sub_f32_e32 v135, v135, v216
	v_sub_f32_e32 v136, v136, v216
	v_sub_f32_e32 v137, v137, v216
	v_sub_f32_e32 v138, v138, v216
	v_sub_f32_e32 v139, v139, v216
	v_sub_f32_e32 v140, v140, v216
	v_sub_f32_e32 v141, v141, v216
	v_sub_f32_e32 v142, v142, v216
	v_sub_f32_e32 v143, v143, v216
	v_sub_f32_e32 v144, v144, v216
	v_sub_f32_e32 v145, v145, v216
	v_mul_f32_e32 v213, v213, v217
	v_mul_f32_e32 v214, v214, v217
	v_mul_f32_e32 v2, v2, v217
	v_mul_f32_e32 v3, v3, v217
	v_mul_f32_e32 v4, v4, v217
	v_mul_f32_e32 v5, v5, v217
	v_mul_f32_e32 v6, v6, v217
	v_mul_f32_e32 v7, v7, v217
	v_mul_f32_e32 v8, v8, v217
	v_mul_f32_e32 v9, v9, v217
	v_mul_f32_e32 v10, v10, v217
	v_mul_f32_e32 v11, v11, v217
	v_mul_f32_e32 v12, v12, v217
	v_mul_f32_e32 v13, v13, v217
	v_mul_f32_e32 v14, v14, v217
	v_mul_f32_e32 v15, v15, v217
	v_mul_f32_e32 v16, v16, v217
	v_mul_f32_e32 v17, v17, v217
	v_mul_f32_e32 v18, v18, v217
	v_mul_f32_e32 v19, v19, v217
	v_mul_f32_e32 v20, v20, v217
	v_mul_f32_e32 v21, v21, v217
	v_mul_f32_e32 v22, v22, v217
	v_mul_f32_e32 v23, v23, v217
	v_mul_f32_e32 v24, v24, v217
	v_mul_f32_e32 v25, v25, v217
	v_mul_f32_e32 v26, v26, v217
	v_mul_f32_e32 v27, v27, v217
	v_mul_f32_e32 v28, v28, v217
	v_mul_f32_e32 v29, v29, v217
	v_mul_f32_e32 v30, v30, v217
	v_mul_f32_e32 v31, v31, v217
	v_mul_f32_e32 v32, v32, v217
	v_mul_f32_e32 v33, v33, v217
.Lna_nr_c2:
	s_waitcnt lgkmcnt(0)
	s_barrier
	global_load_dwordx2 v[146:147], v218, s[30:31] offset:0
	global_load_dwordx2 v[148:149], v218, s[30:31] offset:16
	global_load_dwordx2 v[150:151], v218, s[30:31] offset:32
	global_load_dwordx2 v[152:153], v218, s[30:31] offset:48
	global_load_dwordx2 v[154:155], v218, s[30:31] offset:64
	global_load_dwordx2 v[156:157], v218, s[30:31] offset:80
	global_load_dwordx2 v[158:159], v218, s[30:31] offset:96
	global_load_dwordx2 v[160:161], v218, s[30:31] offset:112
	s_mov_b64 s[46:47], s[30:31]
	s_add_i32 s10, s10, s9
	s_cmpk_lt_i32 s10, 0x200
	s_cbranch_scc0 .Lna_nopf
	s_lshr_b32 s36, s10, 4
	s_and_b32 s37, s10, 15
	s_mul_i32 s38, s36, 0x88000
	s_add_u32 s38, s38, 0x4700000
	s_add_u32 s12, s4, s38
	s_addc_u32 s13, s5, 0
	s_add_u32 s38, s38, 0x1100000
	s_add_u32 s14, s4, s38
	s_addc_u32 s15, s5, 0
	s_add_u32 s16, s12, 0x80000
	s_addc_u32 s17, s13, 0
	s_add_u32 s18, s14, 0x2000
	s_addc_u32 s19, s15, 0
	s_lshl_b32 s40, s68, 1
	s_add_i32 s38, s37, -1
	s_cmp_lt_u32 s38, 14
	s_cselect_b32 s22, 12, 8
	s_cselect_b32 s39, 1, 0
	s_lshl_b32 s41, s37, 2
	s_add_i32 s42, s41, -4
	s_max_i32 s42, s42, 0
	s_min_i32 s42, s42, 56
	s_sub_i32 s42, s42, s39
	s_add_i32 s43, s41, s40
	s_add_i32 s23, s43, -4
	s_max_i32 s23, s23, 0
	s_min_i32 s23, s23, 56
	s_add_i32 s62, s43, -3
	s_max_i32 s62, s62, 0
	s_min_i32 s62, s62, 56
	s_sub_i32 s62, s62, s23
	s_add_i32 s63, s62, 8
	s_sub_i32 s23, s23, s42
	s_sub_i32 s43, s42, s43
	s_add_i32 s43, s43, 7
	s_mul_i32 s25, s43, 0x150
	s_ashr_i32 s43, s42, 31
	s_lshl_b64 s[44:45], s[42:43], 13
	s_add_u32 s12, s12, s44
	s_addc_u32 s13, s13, s45
	s_lshl_b64 s[44:45], s[42:43], 7
	s_add_u32 s14, s14, s44
	s_addc_u32 s15, s15, s45
	s_lshl_b32 s38, s36, 12
	s_lshl_b32 s39, s37, 8
	s_add_u32 s38, s38, s39
	s_lshl_b32 s38, s38, 7
	s_add_u32 s38, s38, 0x6900000
	s_add_u32 s34, s4, s38
	s_addc_u32 s35, s5, 0
	s_lshr_b32 s38, s36, 3
	s_lshl_b32 s38, s38, 12
	s_add_u32 s38, s38, s39
	s_lshl_b32 s38, s38, 10
	s_and_b32 s40, s36, 7
	s_lshl_b32 s40, s40, 7
	s_add_u32 s38, s38, s40
	s_add_u32 s38, s38, 0x8900000
	s_add_u32 s30, s4, s38
	s_addc_u32 s31, s5, 0
	global_load_dwordx4 v[98:101], v219, s[34:35] offset:0
	global_load_dwordx4 v[102:105], v219, s[34:35] offset:32
	global_load_dwordx4 v[106:109], v219, s[34:35] offset:64
	global_load_dwordx4 v[110:113], v219, s[34:35] offset:96
	global_load_dwordx4 v[34:37], v206, s[12:13]
	s_add_u32 s12, s12, 0x2000
	s_addc_u32 s13, s13, 0
	global_load_dwordx4 v[230:233], v206, s[12:13]
	global_load_dwordx4 v[234:237], v207, s[14:15]
	s_add_u32 s12, s12, 0x2000
	s_addc_u32 s13, s13, 0
	s_add_u32 s14, s14, 0x80
	s_addc_u32 s15, s15, 0
	global_load_dwordx4 v[188:191], v206, s[12:13]
	global_load_dwordx4 v[192:195], v207, s[14:15]
	s_add_u32 s12, s12, 0x2000
	s_addc_u32 s13, s13, 0
	s_add_u32 s14, s14, 0x80
	s_addc_u32 s15, s15, 0
	s_mov_b32 s20, 3
	s_mov_b32 s21, 2
.Lna_nopf:
	v_exp_f32_e32 v66, v66
	v_exp_f32_e32 v67, v67
	v_exp_f32_e32 v68, v68
	v_exp_f32_e32 v69, v69
	v_add_f32_e32 v213, v213, v66
	v_add_f32_e32 v214, v214, v67
	v_add_f32_e32 v213, v213, v68
	v_add_f32_e32 v214, v214, v69
	v_exp_f32_e32 v70, v70
	ds_read_b64 v[162:163], v202 offset:8704
	ds_read_b64 v[164:165], v202 offset:8720
	ds_read_b64 v[166:167], v202 offset:13056
	ds_read_b64 v[168:169], v202 offset:13072
	ds_read_b64 v[170:171], v202 offset:8736
	ds_read_b64 v[172:173], v202 offset:8752
	ds_read_b64 v[174:175], v202 offset:13088
	ds_read_b64 v[176:177], v202 offset:13104
	v_exp_f32_e32 v71, v71
	v_exp_f32_e32 v72, v72
	v_exp_f32_e32 v73, v73
	v_add_f32_e32 v213, v213, v70
	v_add_f32_e32 v214, v214, v71
	v_add_f32_e32 v213, v213, v72
	v_add_f32_e32 v214, v214, v73
	v_cvt_pk_bf16_f32 v66, v66, v67
	v_cvt_pk_bf16_f32 v67, v68, v69
	v_cvt_pk_bf16_f32 v68, v70, v71
	v_cvt_pk_bf16_f32 v69, v72, v73
	s_waitcnt lgkmcnt(6)
	s_nop 0
	v_mfma_f32_32x32x16_bf16 v[2:17], v[162:165], v[66:69], v[2:17]
	ds_read_b64 v[162:163], v202 offset:8768
	ds_read_b64 v[164:165], v202 offset:8784
	s_waitcnt lgkmcnt(6)
	v_mfma_f32_32x32x16_bf16 v[18:33], v[166:169], v[66:69], v[18:33]
	ds_read_b64 v[166:167], v202 offset:13120
	ds_read_b64 v[168:169], v202 offset:13136
	v_exp_f32_e32 v74, v74
	v_exp_f32_e32 v75, v75
	v_exp_f32_e32 v76, v76
	v_exp_f32_e32 v77, v77
	v_add_f32_e32 v213, v213, v74
	v_add_f32_e32 v214, v214, v75
	v_add_f32_e32 v213, v213, v76
	v_add_f32_e32 v214, v214, v77
	v_exp_f32_e32 v78, v78
	v_exp_f32_e32 v79, v79
	v_exp_f32_e32 v80, v80
	v_exp_f32_e32 v81, v81
	v_add_f32_e32 v213, v213, v78
	v_add_f32_e32 v214, v214, v79
	v_add_f32_e32 v213, v213, v80
	v_add_f32_e32 v214, v214, v81
	v_cvt_pk_bf16_f32 v74, v74, v75
	v_cvt_pk_bf16_f32 v75, v76, v77
	v_cvt_pk_bf16_f32 v76, v78, v79
	v_cvt_pk_bf16_f32 v77, v80, v81
	s_waitcnt lgkmcnt(6)
	s_nop 0
	v_mfma_f32_32x32x16_bf16 v[2:17], v[170:173], v[74:77], v[2:17]
	ds_read_b64 v[170:171], v202 offset:8800
	ds_read_b64 v[172:173], v202 offset:8816
	s_waitcnt lgkmcnt(6)
	v_mfma_f32_32x32x16_bf16 v[18:33], v[174:177], v[74:77], v[18:33]
	ds_read_b64 v[174:175], v202 offset:13152
	ds_read_b64 v[176:177], v202 offset:13168
	v_exp_f32_e32 v82, v82
	v_exp_f32_e32 v83, v83
	v_exp_f32_e32 v84, v84
	v_exp_f32_e32 v85, v85
	v_add_f32_e32 v213, v213, v82
	v_add_f32_e32 v214, v214, v83
	v_add_f32_e32 v213, v213, v84
	v_add_f32_e32 v214, v214, v85
	v_exp_f32_e32 v86, v86
	v_exp_f32_e32 v87, v87
	v_exp_f32_e32 v88, v88
	v_exp_f32_e32 v89, v89
	v_add_f32_e32 v213, v213, v86
	v_add_f32_e32 v214, v214, v87
	v_add_f32_e32 v213, v213, v88
	v_add_f32_e32 v214, v214, v89
	v_cvt_pk_bf16_f32 v82, v82, v83
	v_cvt_pk_bf16_f32 v83, v84, v85
	v_cvt_pk_bf16_f32 v84, v86, v87
	v_cvt_pk_bf16_f32 v85, v88, v89
	s_waitcnt lgkmcnt(6)
	s_nop 0
	v_mfma_f32_32x32x16_bf16 v[2:17], v[162:165], v[82:85], v[2:17]
	s_waitcnt lgkmcnt(4)
	v_mfma_f32_32x32x16_bf16 v[18:33], v[166:169], v[82:85], v[18:33]
	v_exp_f32_e32 v90, v90
	v_exp_f32_e32 v91, v91
	v_exp_f32_e32 v92, v92
	v_exp_f32_e32 v93, v93
	v_add_f32_e32 v213, v213, v90
	v_add_f32_e32 v214, v214, v91
	v_add_f32_e32 v213, v213, v92
	v_add_f32_e32 v214, v214, v93
	v_exp_f32_e32 v94, v94
	v_exp_f32_e32 v95, v95
	v_exp_f32_e32 v96, v96
	v_exp_f32_e32 v97, v97
	v_add_f32_e32 v213, v213, v94
	v_add_f32_e32 v214, v214, v95
	v_add_f32_e32 v213, v213, v96
	v_add_f32_e32 v214, v214, v97
	v_cvt_pk_bf16_f32 v90, v90, v91
	v_cvt_pk_bf16_f32 v91, v92, v93
	v_cvt_pk_bf16_f32 v92, v94, v95
	v_cvt_pk_bf16_f32 v93, v96, v97
	s_waitcnt lgkmcnt(2)
	s_nop 0
	v_mfma_f32_32x32x16_bf16 v[2:17], v[170:173], v[90:93], v[2:17]
	s_waitcnt lgkmcnt(0)
	v_mfma_f32_32x32x16_bf16 v[18:33], v[174:177], v[90:93], v[18:33]
	s_waitcnt lgkmcnt(0)
	s_barrier
	v_add_f32_e32 v213, v213, v214
	v_mov_b32_e32 v217, v213
	s_nop 1
	v_permlane32_swap_b32_e32 v213, v217
	v_add_f32_e32 v216, v213, v217
	v_div_scale_f32 v217, s[36:37], v216, v216, 1.0
	v_rcp_f32_e32 v223, v217
	v_div_scale_f32 v224, vcc, 1.0, v216, 1.0
	v_fma_f32 v225, -v217, v223, 1.0
	v_fmac_f32_e32 v223, v225, v223
	v_mul_f32_e32 v225, v224, v223
	v_fma_f32 v226, -v217, v225, v224
	v_fmac_f32_e32 v225, v226, v223
	v_fma_f32 v217, -v217, v225, v224
	v_div_fmas_f32 v217, v217, v223, v225
	v_div_fixup_f32 v216, v217, v216, 1.0
	s_nop 15
	v_mul_f32_e32 v2, v2, v216
	v_mul_f32_e32 v3, v3, v216
	v_mul_f32_e32 v4, v4, v216
	v_mul_f32_e32 v5, v5, v216
	v_mul_f32_e32 v6, v6, v216
	v_mul_f32_e32 v7, v7, v216
	v_mul_f32_e32 v8, v8, v216
	v_mul_f32_e32 v9, v9, v216
	v_mul_f32_e32 v10, v10, v216
	v_mul_f32_e32 v11, v11, v216
	v_mul_f32_e32 v12, v12, v216
	v_mul_f32_e32 v13, v13, v216
	v_mul_f32_e32 v14, v14, v216
	v_mul_f32_e32 v15, v15, v216
	v_mul_f32_e32 v16, v16, v216
	v_mul_f32_e32 v17, v17, v216
	v_mul_f32_e32 v18, v18, v216
	v_mul_f32_e32 v19, v19, v216
	v_mul_f32_e32 v20, v20, v216
	v_mul_f32_e32 v21, v21, v216
	v_mul_f32_e32 v22, v22, v216
	v_mul_f32_e32 v23, v23, v216
	v_mul_f32_e32 v24, v24, v216
	v_mul_f32_e32 v25, v25, v216
	v_mul_f32_e32 v26, v26, v216
	v_mul_f32_e32 v27, v27, v216
	v_mul_f32_e32 v28, v28, v216
	v_mul_f32_e32 v29, v29, v216
	v_mul_f32_e32 v30, v30, v216
	v_mul_f32_e32 v31, v31, v216
	v_mul_f32_e32 v32, v32, v216
	v_mul_f32_e32 v33, v33, v216
	s_cmpk_lt_i32 s10, 0x200
	s_cbranch_scc1 .Lna_zw9
	s_waitcnt vmcnt(0)
	s_branch .Lna_zw

.Lna_zw:
	v_lshlrev_b32_e32 v223, 16, v146
	v_and_b32_e32 v224, 0xffff0000, v146
	v_lshlrev_b32_e32 v225, 16, v147
	v_and_b32_e32 v226, 0xffff0000, v147
	v_mul_f32_e32 v2, v2, v223
	v_mul_f32_e32 v3, v3, v224
	v_mul_f32_e32 v4, v4, v225
	v_mul_f32_e32 v5, v5, v226
	v_cvt_pk_bf16_f32 v146, v2, v3
	v_cvt_pk_bf16_f32 v147, v4, v5
	global_store_dwordx2 v218, v[146:147], s[46:47] offset:0
	v_lshlrev_b32_e32 v223, 16, v148
	v_and_b32_e32 v224, 0xffff0000, v148
	v_lshlrev_b32_e32 v225, 16, v149
	v_and_b32_e32 v226, 0xffff0000, v149
	v_mul_f32_e32 v6, v6, v223
	v_mul_f32_e32 v7, v7, v224
	v_mul_f32_e32 v8, v8, v225
	v_mul_f32_e32 v9, v9, v226
	v_cvt_pk_bf16_f32 v148, v6, v7
	v_cvt_pk_bf16_f32 v149, v8, v9
	global_store_dwordx2 v218, v[148:149], s[46:47] offset:16
	v_lshlrev_b32_e32 v223, 16, v150
	v_and_b32_e32 v224, 0xffff0000, v150
	v_lshlrev_b32_e32 v225, 16, v151
	v_and_b32_e32 v226, 0xffff0000, v151
	v_mul_f32_e32 v10, v10, v223
	v_mul_f32_e32 v11, v11, v224
	v_mul_f32_e32 v12, v12, v225
	v_mul_f32_e32 v13, v13, v226
	v_cvt_pk_bf16_f32 v150, v10, v11
	v_cvt_pk_bf16_f32 v151, v12, v13
	global_store_dwordx2 v218, v[150:151], s[46:47] offset:32
	v_lshlrev_b32_e32 v223, 16, v152
	v_and_b32_e32 v224, 0xffff0000, v152
	v_lshlrev_b32_e32 v225, 16, v153
	v_and_b32_e32 v226, 0xffff0000, v153
	v_mul_f32_e32 v14, v14, v223
	v_mul_f32_e32 v15, v15, v224
	v_mul_f32_e32 v16, v16, v225
	v_mul_f32_e32 v17, v17, v226
	v_cvt_pk_bf16_f32 v152, v14, v15
	v_cvt_pk_bf16_f32 v153, v16, v17
	global_store_dwordx2 v218, v[152:153], s[46:47] offset:48
	v_lshlrev_b32_e32 v223, 16, v154
	v_and_b32_e32 v224, 0xffff0000, v154
	v_lshlrev_b32_e32 v225, 16, v155
	v_and_b32_e32 v226, 0xffff0000, v155
	v_mul_f32_e32 v18, v18, v223
	v_mul_f32_e32 v19, v19, v224
	v_mul_f32_e32 v20, v20, v225
	v_mul_f32_e32 v21, v21, v226
	v_cvt_pk_bf16_f32 v154, v18, v19
	v_cvt_pk_bf16_f32 v155, v20, v21
	global_store_dwordx2 v218, v[154:155], s[46:47] offset:64
	v_lshlrev_b32_e32 v223, 16, v156
	v_and_b32_e32 v224, 0xffff0000, v156
	v_lshlrev_b32_e32 v225, 16, v157
	v_and_b32_e32 v226, 0xffff0000, v157
	v_mul_f32_e32 v22, v22, v223
	v_mul_f32_e32 v23, v23, v224
	v_mul_f32_e32 v24, v24, v225
	v_mul_f32_e32 v25, v25, v226
	v_cvt_pk_bf16_f32 v156, v22, v23
	v_cvt_pk_bf16_f32 v157, v24, v25
	global_store_dwordx2 v218, v[156:157], s[46:47] offset:80
	v_lshlrev_b32_e32 v223, 16, v158
	v_and_b32_e32 v224, 0xffff0000, v158
	v_lshlrev_b32_e32 v225, 16, v159
	v_and_b32_e32 v226, 0xffff0000, v159
	v_mul_f32_e32 v26, v26, v223
	v_mul_f32_e32 v27, v27, v224
	v_mul_f32_e32 v28, v28, v225
	v_mul_f32_e32 v29, v29, v226
	v_cvt_pk_bf16_f32 v158, v26, v27
	v_cvt_pk_bf16_f32 v159, v28, v29
	global_store_dwordx2 v218, v[158:159], s[46:47] offset:96
	v_lshlrev_b32_e32 v223, 16, v160
	v_and_b32_e32 v224, 0xffff0000, v160
	v_lshlrev_b32_e32 v225, 16, v161
	v_and_b32_e32 v226, 0xffff0000, v161
	v_mul_f32_e32 v30, v30, v223
	v_mul_f32_e32 v31, v31, v224
	v_mul_f32_e32 v32, v32, v225
	v_mul_f32_e32 v33, v33, v226
	v_cvt_pk_bf16_f32 v160, v30, v31
	v_cvt_pk_bf16_f32 v161, v32, v33
	global_store_dwordx2 v218, v[160:161], s[46:47] offset:112
	s_cmpk_lt_i32 s10, 0x200
	s_cbranch_scc0 .Lna_exit
	v_mov_b32_e32 v2, 0
	v_mov_b32_e32 v3, 0
	v_mov_b32_e32 v4, 0
	v_mov_b32_e32 v5, 0
	v_mov_b32_e32 v6, 0
	v_mov_b32_e32 v7, 0
	v_mov_b32_e32 v8, 0
	v_mov_b32_e32 v9, 0
	v_mov_b32_e32 v10, 0
	v_mov_b32_e32 v11, 0
	v_mov_b32_e32 v12, 0
	v_mov_b32_e32 v13, 0
	v_mov_b32_e32 v14, 0
	v_mov_b32_e32 v15, 0
	v_mov_b32_e32 v16, 0
	v_mov_b32_e32 v17, 0
	v_mov_b32_e32 v18, 0
	v_mov_b32_e32 v19, 0
	v_mov_b32_e32 v20, 0
	v_mov_b32_e32 v21, 0
	v_mov_b32_e32 v22, 0
	v_mov_b32_e32 v23, 0
	v_mov_b32_e32 v24, 0
	v_mov_b32_e32 v25, 0
	v_mov_b32_e32 v26, 0
	v_mov_b32_e32 v27, 0
	v_mov_b32_e32 v28, 0
	v_mov_b32_e32 v29, 0
	v_mov_b32_e32 v30, 0
	v_mov_b32_e32 v31, 0
	v_mov_b32_e32 v32, 0
	v_mov_b32_e32 v33, 0
	v_mov_b32_e32 v212, 0
	v_mov_b32_e32 v213, 0
	v_mov_b32_e32 v214, 0
	v_mov_b32_e32 v220, 0xff7fffff
	v_mov_b32_e32 v221, 0
	s_mov_b64 s[26:27], -1
	v_and_b32_e32 v216, 15, v0
	v_bfe_u32 v217, v0, 5, 1
	s_lshl_b32 s36, s11, 4
	v_add_u32_e32 v222, s36, v216
	v_subrev_u32_e32 v223, 8, v222
	v_med3_i32 v223, v223, 0, 48
	v_lshl_add_u32 v224, v217, 2, s66
	v_sub_u32_e32 v224, v224, v223
	v_add_u32_e32 v225, 0, v224
	v_cmp_gt_u32_e32 vcc, 16, v225
	s_nop 1
	v_cndmask_b32_e32 v114, v229, v228, vcc
	v_add_u32_e32 v225, 1, v224
	v_cmp_gt_u32_e32 vcc, 16, v225
	s_nop 1
	v_cndmask_b32_e32 v115, v229, v228, vcc
	v_add_u32_e32 v225, 2, v224
	v_cmp_gt_u32_e32 vcc, 16, v225
	s_nop 1
	v_cndmask_b32_e32 v116, v229, v228, vcc
	v_add_u32_e32 v225, 3, v224
	v_cmp_gt_u32_e32 vcc, 16, v225
	s_nop 1
	v_cndmask_b32_e32 v117, v229, v228, vcc
	v_add_u32_e32 v225, 8, v224
	v_cmp_gt_u32_e32 vcc, 16, v225
	s_nop 1
	v_cndmask_b32_e32 v118, v229, v228, vcc
	v_add_u32_e32 v225, 9, v224
	v_cmp_gt_u32_e32 vcc, 16, v225
	s_nop 1
	v_cndmask_b32_e32 v119, v229, v228, vcc
	v_add_u32_e32 v225, 10, v224
	v_cmp_gt_u32_e32 vcc, 16, v225
	s_nop 1
	v_cndmask_b32_e32 v120, v229, v228, vcc
	v_add_u32_e32 v225, 11, v224
	v_cmp_gt_u32_e32 vcc, 16, v225
	s_nop 1
	v_cndmask_b32_e32 v121, v229, v228, vcc
	v_add_u32_e32 v225, 16, v224
	v_cmp_gt_u32_e32 vcc, 16, v225
	s_nop 1
	v_cndmask_b32_e32 v122, v229, v228, vcc
	v_add_u32_e32 v225, 17, v224
	v_cmp_gt_u32_e32 vcc, 16, v225
	s_nop 1
	v_cndmask_b32_e32 v123, v229, v228, vcc
	v_add_u32_e32 v225, 18, v224
	v_cmp_gt_u32_e32 vcc, 16, v225
	s_nop 1
	v_cndmask_b32_e32 v124, v229, v228, vcc
	v_add_u32_e32 v225, 19, v224
	v_cmp_gt_u32_e32 vcc, 16, v225
	s_nop 1
	v_cndmask_b32_e32 v125, v229, v228, vcc
	v_add_u32_e32 v225, 24, v224
	v_cmp_gt_u32_e32 vcc, 16, v225
	s_nop 1
	v_cndmask_b32_e32 v126, v229, v228, vcc
	v_add_u32_e32 v225, 25, v224
	v_cmp_gt_u32_e32 vcc, 16, v225
	s_nop 1
	v_cndmask_b32_e32 v127, v229, v228, vcc
	v_add_u32_e32 v225, 26, v224
	v_cmp_gt_u32_e32 vcc, 16, v225
	s_nop 1
	v_cndmask_b32_e32 v128, v229, v228, vcc
	v_add_u32_e32 v225, 27, v224
	v_cmp_gt_u32_e32 vcc, 16, v225
	s_nop 1
	v_cndmask_b32_e32 v129, v229, v228, vcc
	s_waitcnt vmcnt(12)
	s_branch .Lna_stage
